# RWKV scan: output-reduction DPP chain interleaved with the next step's S.a partial products (nops removed) in 10 steps
# baseline (speedup 1.0000x reference)
.LBB0_595:
	s_andn2_saveexec_b64 s[0:1], s[20:21]
	s_cbranch_execz .LBB0_609
	s_bitcmp1_b32 s25, 0
	s_cselect_b32 s20, 0x6000, 0
	v_add_u32_e32 v1, s20, v143
	ds_read_b128 v[32:35], v1
	ds_read_b128 v[40:43], v1 offset:16
	s_and_b32 s20, s25, 1
	s_mul_i32 s21, s20, 0x6000
	s_add_i32 s21, s21, 0
	s_waitcnt lgkmcnt(1)
	v_pk_mul_f32 v[2:3], v[66:67], v[34:35] op_sel_hi:[1,0]
	v_pk_mul_f32 v[34:35], v[64:65], v[34:35] op_sel:[0,1]
	v_pk_fma_f32 v[2:3], v[70:71], v[32:33], v[2:3] op_sel_hi:[1,0,1]
	v_pk_fma_f32 v[32:33], v[68:69], v[32:33], v[34:35] op_sel:[0,1,0]
	s_waitcnt lgkmcnt(0)
	v_pk_fma_f32 v[2:3], v[62:63], v[40:41], v[2:3] op_sel_hi:[1,0,1]
	v_pk_fma_f32 v[32:33], v[60:61], v[40:41], v[32:33] op_sel:[0,1,0]
	v_pk_fma_f32 v[2:3], v[46:47], v[42:43], v[2:3] op_sel_hi:[1,0,1]
	v_pk_fma_f32 v[32:33], v[44:45], v[42:43], v[32:33] op_sel:[0,1,0]
	v_lshl_add_u32 v152, v97, 2, s21
	v_pk_add_f32 v[2:3], v[2:3], v[32:33]
	v_lshl_add_u32 v151, v98, 2, s21
	ds_read_b128 v[72:75], v152 offset:4096
	ds_read_b128 v[154:157], v152 offset:4112
	ds_read_b128 v[158:161], v152 offset:8192
	ds_read_b128 v[166:169], v152 offset:8208
	ds_read_b128 v[170:173], v152 offset:12288
	ds_read_b128 v[174:177], v152 offset:12304
	ds_read_b128 v[178:181], v152 offset:16384
	ds_read_b128 v[198:201], v152 offset:16400
	ds_read_b64 v[202:203], v151 offset:20480
	ds_read_b128 v[36:39], v1 offset:256
	ds_read_b128 v[28:31], v1 offset:272
	v_add_f32_dpp v2, v2, v2 quad_perm:[1,0,3,2] row_mask:0xf bank_mask:0xf bound_ctrl:1
	v_add_f32_dpp v3, v3, v3 quad_perm:[1,0,3,2] row_mask:0xf bank_mask:0xf bound_ctrl:1
	s_lshl_b32 s20, s20, 12
	v_add_u32_e32 v153, s20, v99
	v_add_f32_dpp v2, v2, v2 quad_perm:[2,3,0,1] row_mask:0xf bank_mask:0xf bound_ctrl:1
	v_add_f32_dpp v3, v3, v3 quad_perm:[2,3,0,1] row_mask:0xf bank_mask:0xf bound_ctrl:1
	s_nop 0
	v_add_f32_dpp v32, v2, v2 row_half_mirror row_mask:0xf bank_mask:0xf bound_ctrl:1
	v_add_f32_dpp v33, v3, v3 row_half_mirror row_mask:0xf bank_mask:0xf bound_ctrl:1
	s_waitcnt lgkmcnt(8)
	v_pk_mul_f32 v[2:3], v[158:159], v[32:33] op_sel_hi:[0,1]
	s_waitcnt lgkmcnt(2)
	ds_read_b128 v[208:211], v152 offset:4352
	ds_read_b128 v[212:215], v152 offset:4368
	ds_read_b128 v[216:219], v152 offset:8448
	ds_read_b128 v[220:223], v152 offset:8464
	ds_read_b128 v[224:227], v152 offset:12544
	ds_read_b128 v[228:231], v152 offset:12560
	ds_read_b128 v[232:235], v152 offset:16640
	ds_read_b128 v[236:239], v152 offset:16656
	ds_read_b64 v[240:241], v151 offset:20736
	v_pk_fma_f32 v[2:3], v[170:171], v[202:203], v[2:3] op_sel_hi:[0,1,1] neg_lo:[0,0,1] neg_hi:[0,0,1]
	v_pk_mul_f32 v[34:35], v[158:159], v[32:33] op_sel:[1,0]
	v_pk_fma_f32 v[2:3], v[70:71], v[72:73], v[2:3] op_sel_hi:[1,0,1]
	v_pk_fma_f32 v[34:35], v[170:171], v[202:203], v[34:35] op_sel:[1,0,0] neg_lo:[0,0,1] neg_hi:[0,0,1]
	v_pk_mul_f32 v[42:43], v[160:161], v[32:33] op_sel_hi:[0,1]
	v_pk_fma_f32 v[68:69], v[68:69], v[72:73], v[34:35] op_sel:[0,1,0]
	v_pk_fma_f32 v[42:43], v[172:173], v[202:203], v[42:43] op_sel_hi:[0,1,1] neg_lo:[0,0,1] neg_hi:[0,0,1]
	v_pk_mul_f32 v[70:71], v[160:161], v[32:33] op_sel:[1,0]
	v_pk_fma_f32 v[66:67], v[66:67], v[74:75], v[42:43] op_sel_hi:[1,0,1]
	v_pk_fma_f32 v[70:71], v[172:173], v[202:203], v[70:71] op_sel:[1,0,0] neg_lo:[0,0,1] neg_hi:[0,0,1]
	v_pk_fma_f32 v[40:41], v[178:179], v[68:69], 0 op_sel:[1,0,0] op_sel_hi:[1,1,0]
	v_pk_fma_f32 v[64:65], v[64:65], v[74:75], v[70:71] op_sel:[0,1,0]
	v_pk_fma_f32 v[40:41], v[180:181], v[64:65], v[40:41] op_sel:[1,0,0]
	v_pk_mul_f32 v[42:43], v[166:167], v[32:33] op_sel_hi:[0,1]
	v_pk_fma_f32 v[42:43], v[174:175], v[202:203], v[42:43] op_sel_hi:[0,1,1] neg_lo:[0,0,1] neg_hi:[0,0,1]
	v_pk_fma_f32 v[62:63], v[62:63], v[154:155], v[42:43] op_sel_hi:[1,0,1]
	v_pk_mul_f32 v[42:43], v[166:167], v[32:33] op_sel:[1,0]
	v_pk_fma_f32 v[34:35], v[178:179], v[2:3], 0 op_sel_hi:[0,1,0]
	v_pk_fma_f32 v[42:43], v[174:175], v[202:203], v[42:43] op_sel:[1,0,0] neg_lo:[0,0,1] neg_hi:[0,0,1]
	v_pk_fma_f32 v[60:61], v[60:61], v[154:155], v[42:43] op_sel:[0,1,0]
	v_pk_mul_f32 v[42:43], v[168:169], v[32:33] op_sel_hi:[0,1]
	v_pk_fma_f32 v[34:35], v[180:181], v[66:67], v[34:35] op_sel_hi:[0,1,1]
	v_pk_fma_f32 v[42:43], v[176:177], v[202:203], v[42:43] op_sel_hi:[0,1,1] neg_lo:[0,0,1] neg_hi:[0,0,1]
	v_pk_mul_f32 v[32:33], v[168:169], v[32:33] op_sel:[1,0]
	v_pk_fma_f32 v[34:35], v[198:199], v[62:63], v[34:35] op_sel_hi:[0,1,1]
	v_pk_fma_f32 v[46:47], v[46:47], v[156:157], v[42:43] op_sel_hi:[1,0,1]
	v_pk_fma_f32 v[32:33], v[176:177], v[202:203], v[32:33] op_sel:[1,0,0] neg_lo:[0,0,1] neg_hi:[0,0,1]
	v_pk_fma_f32 v[40:41], v[198:199], v[60:61], v[40:41] op_sel:[1,0,0]
	v_pk_fma_f32 v[44:45], v[44:45], v[156:157], v[32:33] op_sel:[0,1,0]
	v_pk_fma_f32 v[32:33], v[200:201], v[46:47], v[34:35] op_sel_hi:[0,1,1]
	v_pk_fma_f32 v[34:35], v[200:201], v[44:45], v[40:41] op_sel:[1,0,0]
	v_pk_add_f32 v[32:33], v[32:33], v[34:35]
	s_waitcnt lgkmcnt(1)
	v_pk_mul_f32 v[202:203], v[38:39], v[66:67] op_sel_hi:[0,1]
	v_pk_fma_f32 v[202:203], v[36:37], v[2:3], v[202:203] op_sel_hi:[0,1,1]
	v_add_f32_dpp v32, v32, v32 quad_perm:[1,0,3,2] row_mask:0xf bank_mask:0xf bound_ctrl:1
	v_add_f32_dpp v33, v33, v33 quad_perm:[1,0,3,2] row_mask:0xf bank_mask:0xf bound_ctrl:1
	v_pk_mul_f32 v[38:39], v[38:39], v[64:65] op_sel:[1,0]
	v_pk_fma_f32 v[36:37], v[36:37], v[68:69], v[38:39] op_sel:[1,0,0]
	v_add_f32_dpp v32, v32, v32 quad_perm:[2,3,0,1] row_mask:0xf bank_mask:0xf bound_ctrl:1
	v_add_f32_dpp v33, v33, v33 quad_perm:[2,3,0,1] row_mask:0xf bank_mask:0xf bound_ctrl:1
	s_waitcnt lgkmcnt(0)
	v_pk_fma_f32 v[38:39], v[28:29], v[62:63], v[202:203] op_sel_hi:[0,1,1]
	v_pk_fma_f32 v[28:29], v[28:29], v[60:61], v[36:37] op_sel:[1,0,0]
	v_add_f32_dpp v32, v32, v32 row_half_mirror row_mask:0xf bank_mask:0xf bound_ctrl:1
	v_add_f32_dpp v33, v33, v33 row_half_mirror row_mask:0xf bank_mask:0xf bound_ctrl:1
	v_pk_fma_f32 v[36:37], v[30:31], v[46:47], v[38:39] op_sel_hi:[0,1,1]
	v_pk_fma_f32 v[28:29], v[30:31], v[44:45], v[28:29] op_sel:[1,0,0]
	s_and_saveexec_b64 s[20:21], s[14:15]
	ds_write_b64 v153, v[32:33] offset:49152
	s_or_b64 exec, exec, s[20:21]
	v_pk_add_f32 v[28:29], v[36:37], v[28:29]
	ds_read_b128 v[100:103], v152 offset:4608
	ds_read_b128 v[104:107], v152 offset:4624
	ds_read_b128 v[108:111], v152 offset:8704
	ds_read_b128 v[112:115], v152 offset:8720
	ds_read_b128 v[116:119], v152 offset:12800
	ds_read_b128 v[120:123], v152 offset:12816
	ds_read_b128 v[124:127], v152 offset:16896
	ds_read_b128 v[128:131], v152 offset:16912
	ds_read_b64 v[132:133], v151 offset:20992
	ds_read_b128 v[40:43], v1 offset:512
	ds_read_b128 v[32:35], v1 offset:528
	v_add_f32_dpp v28, v28, v28 quad_perm:[1,0,3,2] row_mask:0xf bank_mask:0xf bound_ctrl:1
	v_add_f32_dpp v29, v29, v29 quad_perm:[1,0,3,2] row_mask:0xf bank_mask:0xf bound_ctrl:1
	s_nop 0
	v_add_f32_dpp v28, v28, v28 quad_perm:[2,3,0,1] row_mask:0xf bank_mask:0xf bound_ctrl:1
	v_add_f32_dpp v29, v29, v29 quad_perm:[2,3,0,1] row_mask:0xf bank_mask:0xf bound_ctrl:1
	s_nop 0
	v_add_f32_dpp v28, v28, v28 row_half_mirror row_mask:0xf bank_mask:0xf bound_ctrl:1
	v_add_f32_dpp v29, v29, v29 row_half_mirror row_mask:0xf bank_mask:0xf bound_ctrl:1
	v_pk_mul_f32 v[30:31], v[216:217], v[28:29] op_sel_hi:[0,1]
	v_pk_fma_f32 v[30:31], v[224:225], v[240:241], v[30:31] op_sel_hi:[0,1,1] neg_lo:[0,0,1] neg_hi:[0,0,1]
	v_pk_fma_f32 v[2:3], v[2:3], v[208:209], v[30:31] op_sel_hi:[1,0,1]
	v_pk_mul_f32 v[30:31], v[216:217], v[28:29] op_sel:[1,0]
	v_pk_mul_f32 v[38:39], v[218:219], v[28:29] op_sel_hi:[0,1]
	v_pk_fma_f32 v[30:31], v[224:225], v[240:241], v[30:31] op_sel:[1,0,0] neg_lo:[0,0,1] neg_hi:[0,0,1]
	v_pk_fma_f32 v[38:39], v[226:227], v[240:241], v[38:39] op_sel_hi:[0,1,1] neg_lo:[0,0,1] neg_hi:[0,0,1]
	v_pk_fma_f32 v[68:69], v[68:69], v[208:209], v[30:31] op_sel:[0,1,0]
	v_pk_fma_f32 v[66:67], v[66:67], v[210:211], v[38:39] op_sel_hi:[1,0,1]
	v_pk_mul_f32 v[70:71], v[218:219], v[28:29] op_sel:[1,0]
	v_pk_fma_f32 v[70:71], v[226:227], v[240:241], v[70:71] op_sel:[1,0,0] neg_lo:[0,0,1] neg_hi:[0,0,1]
	v_pk_fma_f32 v[36:37], v[232:233], v[68:69], 0 op_sel:[1,0,0] op_sel_hi:[1,1,0]
	v_pk_fma_f32 v[64:65], v[64:65], v[210:211], v[70:71] op_sel:[0,1,0]
	v_pk_fma_f32 v[36:37], v[234:235], v[64:65], v[36:37] op_sel:[1,0,0]
	v_pk_mul_f32 v[38:39], v[220:221], v[28:29] op_sel_hi:[0,1]
	v_pk_fma_f32 v[38:39], v[228:229], v[240:241], v[38:39] op_sel_hi:[0,1,1] neg_lo:[0,0,1] neg_hi:[0,0,1]
	v_pk_fma_f32 v[62:63], v[62:63], v[212:213], v[38:39] op_sel_hi:[1,0,1]
	v_pk_mul_f32 v[38:39], v[220:221], v[28:29] op_sel:[1,0]
	v_pk_fma_f32 v[30:31], v[232:233], v[2:3], 0 op_sel_hi:[0,1,0]
	v_pk_fma_f32 v[38:39], v[228:229], v[240:241], v[38:39] op_sel:[1,0,0] neg_lo:[0,0,1] neg_hi:[0,0,1]
	v_pk_fma_f32 v[60:61], v[60:61], v[212:213], v[38:39] op_sel:[0,1,0]
	v_pk_mul_f32 v[38:39], v[222:223], v[28:29] op_sel_hi:[0,1]
	v_pk_fma_f32 v[30:31], v[234:235], v[66:67], v[30:31] op_sel_hi:[0,1,1]
	v_pk_fma_f32 v[38:39], v[230:231], v[240:241], v[38:39] op_sel_hi:[0,1,1] neg_lo:[0,0,1] neg_hi:[0,0,1]
	v_pk_mul_f32 v[28:29], v[222:223], v[28:29] op_sel:[1,0]
	v_pk_fma_f32 v[30:31], v[236:237], v[62:63], v[30:31] op_sel_hi:[0,1,1]
	v_pk_fma_f32 v[46:47], v[46:47], v[214:215], v[38:39] op_sel_hi:[1,0,1]
	v_pk_fma_f32 v[28:29], v[230:231], v[240:241], v[28:29] op_sel:[1,0,0] neg_lo:[0,0,1] neg_hi:[0,0,1]
	v_pk_fma_f32 v[36:37], v[236:237], v[60:61], v[36:37] op_sel:[1,0,0]
	v_pk_fma_f32 v[44:45], v[44:45], v[214:215], v[28:29] op_sel:[0,1,0]
	v_pk_fma_f32 v[28:29], v[238:239], v[46:47], v[30:31] op_sel_hi:[0,1,1]
	v_pk_fma_f32 v[30:31], v[238:239], v[44:45], v[36:37] op_sel:[1,0,0]
	v_pk_add_f32 v[28:29], v[28:29], v[30:31]
	s_waitcnt lgkmcnt(1)
	v_pk_mul_f32 v[202:203], v[42:43], v[66:67] op_sel_hi:[0,1]
	v_pk_fma_f32 v[202:203], v[40:41], v[2:3], v[202:203] op_sel_hi:[0,1,1]
	v_add_f32_dpp v28, v28, v28 quad_perm:[1,0,3,2] row_mask:0xf bank_mask:0xf bound_ctrl:1
	v_add_f32_dpp v29, v29, v29 quad_perm:[1,0,3,2] row_mask:0xf bank_mask:0xf bound_ctrl:1
	v_pk_mul_f32 v[42:43], v[42:43], v[64:65] op_sel:[1,0]
	v_pk_fma_f32 v[40:41], v[40:41], v[68:69], v[42:43] op_sel:[1,0,0]
	v_add_f32_dpp v28, v28, v28 quad_perm:[2,3,0,1] row_mask:0xf bank_mask:0xf bound_ctrl:1
	v_add_f32_dpp v29, v29, v29 quad_perm:[2,3,0,1] row_mask:0xf bank_mask:0xf bound_ctrl:1
	s_waitcnt lgkmcnt(0)
	v_pk_fma_f32 v[42:43], v[32:33], v[62:63], v[202:203] op_sel_hi:[0,1,1]
	v_pk_fma_f32 v[32:33], v[32:33], v[60:61], v[40:41] op_sel:[1,0,0]
	v_add_f32_dpp v28, v28, v28 row_half_mirror row_mask:0xf bank_mask:0xf bound_ctrl:1
	v_add_f32_dpp v29, v29, v29 row_half_mirror row_mask:0xf bank_mask:0xf bound_ctrl:1
	v_pk_fma_f32 v[40:41], v[34:35], v[46:47], v[42:43] op_sel_hi:[0,1,1]
	v_pk_fma_f32 v[32:33], v[34:35], v[44:45], v[32:33] op_sel:[1,0,0]
	s_and_saveexec_b64 s[20:21], s[14:15]
	ds_write_b64 v153, v[28:29] offset:49408
	s_or_b64 exec, exec, s[20:21]
	v_pk_add_f32 v[32:33], v[40:41], v[32:33]
	ds_read_b128 v[208:211], v152 offset:4864
	ds_read_b128 v[212:215], v152 offset:4880
	ds_read_b128 v[216:219], v152 offset:8960
	ds_read_b128 v[220:223], v152 offset:8976
	ds_read_b128 v[224:227], v152 offset:13056
	ds_read_b128 v[228:231], v152 offset:13072
	ds_read_b128 v[232:235], v152 offset:17152
	ds_read_b128 v[236:239], v152 offset:17168
	ds_read_b64 v[240:241], v151 offset:21248
	ds_read_b128 v[36:39], v1 offset:768
	ds_read_b128 v[28:31], v1 offset:784
	v_add_f32_dpp v32, v32, v32 quad_perm:[1,0,3,2] row_mask:0xf bank_mask:0xf bound_ctrl:1
	v_add_f32_dpp v33, v33, v33 quad_perm:[1,0,3,2] row_mask:0xf bank_mask:0xf bound_ctrl:1
	s_nop 0
	v_add_f32_dpp v32, v32, v32 quad_perm:[2,3,0,1] row_mask:0xf bank_mask:0xf bound_ctrl:1
	v_add_f32_dpp v33, v33, v33 quad_perm:[2,3,0,1] row_mask:0xf bank_mask:0xf bound_ctrl:1
	s_nop 0
	v_add_f32_dpp v32, v32, v32 row_half_mirror row_mask:0xf bank_mask:0xf bound_ctrl:1
	v_add_f32_dpp v33, v33, v33 row_half_mirror row_mask:0xf bank_mask:0xf bound_ctrl:1
	v_pk_mul_f32 v[34:35], v[108:109], v[32:33] op_sel_hi:[0,1]
	v_pk_fma_f32 v[34:35], v[116:117], v[132:133], v[34:35] op_sel_hi:[0,1,1] neg_lo:[0,0,1] neg_hi:[0,0,1]
	v_pk_fma_f32 v[2:3], v[2:3], v[100:101], v[34:35] op_sel_hi:[1,0,1]
	v_pk_mul_f32 v[34:35], v[108:109], v[32:33] op_sel:[1,0]
	v_pk_mul_f32 v[42:43], v[110:111], v[32:33] op_sel_hi:[0,1]
	v_pk_fma_f32 v[34:35], v[116:117], v[132:133], v[34:35] op_sel:[1,0,0] neg_lo:[0,0,1] neg_hi:[0,0,1]
	v_pk_fma_f32 v[42:43], v[118:119], v[132:133], v[42:43] op_sel_hi:[0,1,1] neg_lo:[0,0,1] neg_hi:[0,0,1]
	v_pk_fma_f32 v[68:69], v[68:69], v[100:101], v[34:35] op_sel:[0,1,0]
	v_pk_fma_f32 v[66:67], v[66:67], v[102:103], v[42:43] op_sel_hi:[1,0,1]
	v_pk_mul_f32 v[70:71], v[110:111], v[32:33] op_sel:[1,0]
	v_pk_fma_f32 v[70:71], v[118:119], v[132:133], v[70:71] op_sel:[1,0,0] neg_lo:[0,0,1] neg_hi:[0,0,1]
	v_pk_fma_f32 v[40:41], v[124:125], v[68:69], 0 op_sel:[1,0,0] op_sel_hi:[1,1,0]
	v_pk_fma_f32 v[64:65], v[64:65], v[102:103], v[70:71] op_sel:[0,1,0]
	v_pk_fma_f32 v[40:41], v[126:127], v[64:65], v[40:41] op_sel:[1,0,0]
	v_pk_mul_f32 v[42:43], v[112:113], v[32:33] op_sel_hi:[0,1]
	v_pk_fma_f32 v[42:43], v[120:121], v[132:133], v[42:43] op_sel_hi:[0,1,1] neg_lo:[0,0,1] neg_hi:[0,0,1]
	v_pk_fma_f32 v[62:63], v[62:63], v[104:105], v[42:43] op_sel_hi:[1,0,1]
	v_pk_mul_f32 v[42:43], v[112:113], v[32:33] op_sel:[1,0]
	v_pk_fma_f32 v[34:35], v[124:125], v[2:3], 0 op_sel_hi:[0,1,0]
	v_pk_fma_f32 v[42:43], v[120:121], v[132:133], v[42:43] op_sel:[1,0,0] neg_lo:[0,0,1] neg_hi:[0,0,1]
	v_pk_fma_f32 v[60:61], v[60:61], v[104:105], v[42:43] op_sel:[0,1,0]
	v_pk_mul_f32 v[42:43], v[114:115], v[32:33] op_sel_hi:[0,1]
	v_pk_fma_f32 v[34:35], v[126:127], v[66:67], v[34:35] op_sel_hi:[0,1,1]
	v_pk_fma_f32 v[42:43], v[122:123], v[132:133], v[42:43] op_sel_hi:[0,1,1] neg_lo:[0,0,1] neg_hi:[0,0,1]
	v_pk_mul_f32 v[32:33], v[114:115], v[32:33] op_sel:[1,0]
	v_pk_fma_f32 v[34:35], v[128:129], v[62:63], v[34:35] op_sel_hi:[0,1,1]
	v_pk_fma_f32 v[46:47], v[46:47], v[106:107], v[42:43] op_sel_hi:[1,0,1]
	v_pk_fma_f32 v[32:33], v[122:123], v[132:133], v[32:33] op_sel:[1,0,0] neg_lo:[0,0,1] neg_hi:[0,0,1]
	v_pk_fma_f32 v[40:41], v[128:129], v[60:61], v[40:41] op_sel:[1,0,0]
	v_pk_fma_f32 v[44:45], v[44:45], v[106:107], v[32:33] op_sel:[0,1,0]
	v_pk_fma_f32 v[32:33], v[130:131], v[46:47], v[34:35] op_sel_hi:[0,1,1]
	v_pk_fma_f32 v[34:35], v[130:131], v[44:45], v[40:41] op_sel:[1,0,0]
	v_pk_add_f32 v[32:33], v[32:33], v[34:35]
	s_waitcnt lgkmcnt(1)
	v_pk_mul_f32 v[202:203], v[38:39], v[66:67] op_sel_hi:[0,1]
	v_pk_fma_f32 v[202:203], v[36:37], v[2:3], v[202:203] op_sel_hi:[0,1,1]
	v_add_f32_dpp v32, v32, v32 quad_perm:[1,0,3,2] row_mask:0xf bank_mask:0xf bound_ctrl:1
	v_add_f32_dpp v33, v33, v33 quad_perm:[1,0,3,2] row_mask:0xf bank_mask:0xf bound_ctrl:1
	v_pk_mul_f32 v[38:39], v[38:39], v[64:65] op_sel:[1,0]
	v_pk_fma_f32 v[36:37], v[36:37], v[68:69], v[38:39] op_sel:[1,0,0]
	v_add_f32_dpp v32, v32, v32 quad_perm:[2,3,0,1] row_mask:0xf bank_mask:0xf bound_ctrl:1
	v_add_f32_dpp v33, v33, v33 quad_perm:[2,3,0,1] row_mask:0xf bank_mask:0xf bound_ctrl:1
	s_waitcnt lgkmcnt(0)
	v_pk_fma_f32 v[38:39], v[28:29], v[62:63], v[202:203] op_sel_hi:[0,1,1]
	v_pk_fma_f32 v[28:29], v[28:29], v[60:61], v[36:37] op_sel:[1,0,0]
	v_add_f32_dpp v32, v32, v32 row_half_mirror row_mask:0xf bank_mask:0xf bound_ctrl:1
	v_add_f32_dpp v33, v33, v33 row_half_mirror row_mask:0xf bank_mask:0xf bound_ctrl:1
	v_pk_fma_f32 v[36:37], v[30:31], v[46:47], v[38:39] op_sel_hi:[0,1,1]
	v_pk_fma_f32 v[28:29], v[30:31], v[44:45], v[28:29] op_sel:[1,0,0]
	s_and_saveexec_b64 s[20:21], s[14:15]
	ds_write_b64 v153, v[32:33] offset:49664
	s_or_b64 exec, exec, s[20:21]
	v_pk_add_f32 v[28:29], v[36:37], v[28:29]
	ds_read_b128 v[100:103], v152 offset:5120
	ds_read_b128 v[104:107], v152 offset:5136
	ds_read_b128 v[108:111], v152 offset:9216
	ds_read_b128 v[112:115], v152 offset:9232
	ds_read_b128 v[116:119], v152 offset:13312
	ds_read_b128 v[120:123], v152 offset:13328
	ds_read_b128 v[124:127], v152 offset:17408
	ds_read_b128 v[128:131], v152 offset:17424
	ds_read_b64 v[132:133], v151 offset:21504
	ds_read_b128 v[40:43], v1 offset:1024
	ds_read_b128 v[32:35], v1 offset:1040
	v_add_f32_dpp v28, v28, v28 quad_perm:[1,0,3,2] row_mask:0xf bank_mask:0xf bound_ctrl:1
	v_add_f32_dpp v29, v29, v29 quad_perm:[1,0,3,2] row_mask:0xf bank_mask:0xf bound_ctrl:1
	s_nop 0
	v_add_f32_dpp v28, v28, v28 quad_perm:[2,3,0,1] row_mask:0xf bank_mask:0xf bound_ctrl:1
	v_add_f32_dpp v29, v29, v29 quad_perm:[2,3,0,1] row_mask:0xf bank_mask:0xf bound_ctrl:1
	s_nop 0
	v_add_f32_dpp v36, v28, v28 row_half_mirror row_mask:0xf bank_mask:0xf bound_ctrl:1
	v_add_f32_dpp v37, v29, v29 row_half_mirror row_mask:0xf bank_mask:0xf bound_ctrl:1
	v_pk_mul_f32 v[28:29], v[216:217], v[36:37] op_sel_hi:[0,1]
	v_pk_fma_f32 v[28:29], v[224:225], v[240:241], v[28:29] op_sel_hi:[0,1,1] neg_lo:[0,0,1] neg_hi:[0,0,1]
	v_pk_fma_f32 v[2:3], v[2:3], v[208:209], v[28:29] op_sel_hi:[1,0,1]
	v_pk_mul_f32 v[28:29], v[216:217], v[36:37] op_sel:[1,0]
	v_pk_mul_f32 v[30:31], v[218:219], v[36:37] op_sel_hi:[0,1]
	v_pk_fma_f32 v[28:29], v[224:225], v[240:241], v[28:29] op_sel:[1,0,0] neg_lo:[0,0,1] neg_hi:[0,0,1]
	v_pk_fma_f32 v[30:31], v[226:227], v[240:241], v[30:31] op_sel_hi:[0,1,1] neg_lo:[0,0,1] neg_hi:[0,0,1]
	v_pk_fma_f32 v[28:29], v[68:69], v[208:209], v[28:29] op_sel:[0,1,0]
	v_pk_fma_f32 v[30:31], v[66:67], v[210:211], v[30:31] op_sel_hi:[1,0,1]
	v_pk_mul_f32 v[70:71], v[218:219], v[36:37] op_sel:[1,0]
	v_pk_fma_f32 v[70:71], v[226:227], v[240:241], v[70:71] op_sel:[1,0,0] neg_lo:[0,0,1] neg_hi:[0,0,1]
	v_pk_fma_f32 v[68:69], v[232:233], v[28:29], 0 op_sel:[1,0,0] op_sel_hi:[1,1,0]
	v_pk_fma_f32 v[64:65], v[64:65], v[210:211], v[70:71] op_sel:[0,1,0]
	v_pk_fma_f32 v[66:67], v[234:235], v[64:65], v[68:69] op_sel:[1,0,0]
	v_pk_mul_f32 v[68:69], v[220:221], v[36:37] op_sel_hi:[0,1]
	v_pk_fma_f32 v[68:69], v[228:229], v[240:241], v[68:69] op_sel_hi:[0,1,1] neg_lo:[0,0,1] neg_hi:[0,0,1]
	v_pk_fma_f32 v[62:63], v[62:63], v[212:213], v[68:69] op_sel_hi:[1,0,1]
	v_pk_mul_f32 v[68:69], v[220:221], v[36:37] op_sel:[1,0]
	v_pk_fma_f32 v[38:39], v[232:233], v[2:3], 0 op_sel_hi:[0,1,0]
	v_pk_fma_f32 v[68:69], v[228:229], v[240:241], v[68:69] op_sel:[1,0,0] neg_lo:[0,0,1] neg_hi:[0,0,1]
	v_pk_fma_f32 v[38:39], v[234:235], v[30:31], v[38:39] op_sel_hi:[0,1,1]
	v_pk_fma_f32 v[60:61], v[60:61], v[212:213], v[68:69] op_sel:[0,1,0]
	v_pk_fma_f32 v[70:71], v[236:237], v[60:61], v[66:67] op_sel:[1,0,0]
	v_pk_mul_f32 v[66:67], v[222:223], v[36:37] op_sel_hi:[0,1]
	v_pk_fma_f32 v[66:67], v[230:231], v[240:241], v[66:67] op_sel_hi:[0,1,1] neg_lo:[0,0,1] neg_hi:[0,0,1]
	v_pk_mul_f32 v[36:37], v[222:223], v[36:37] op_sel:[1,0]
	v_pk_fma_f32 v[38:39], v[236:237], v[62:63], v[38:39] op_sel_hi:[0,1,1]
	v_pk_fma_f32 v[66:67], v[46:47], v[214:215], v[66:67] op_sel_hi:[1,0,1]
	v_pk_fma_f32 v[36:37], v[230:231], v[240:241], v[36:37] op_sel:[1,0,0] neg_lo:[0,0,1] neg_hi:[0,0,1]
	v_pk_fma_f32 v[68:69], v[44:45], v[214:215], v[36:37] op_sel:[0,1,0]
	v_pk_fma_f32 v[36:37], v[238:239], v[66:67], v[38:39] op_sel_hi:[0,1,1]
	v_pk_fma_f32 v[38:39], v[238:239], v[68:69], v[70:71] op_sel:[1,0,0]
	v_pk_add_f32 v[36:37], v[36:37], v[38:39]
	s_waitcnt lgkmcnt(1)
	v_pk_mul_f32 v[202:203], v[42:43], v[30:31] op_sel_hi:[0,1]
	v_pk_fma_f32 v[202:203], v[40:41], v[2:3], v[202:203] op_sel_hi:[0,1,1]
	v_add_f32_dpp v36, v36, v36 quad_perm:[1,0,3,2] row_mask:0xf bank_mask:0xf bound_ctrl:1
	v_add_f32_dpp v37, v37, v37 quad_perm:[1,0,3,2] row_mask:0xf bank_mask:0xf bound_ctrl:1
	v_pk_mul_f32 v[42:43], v[42:43], v[64:65] op_sel:[1,0]
	v_pk_fma_f32 v[40:41], v[40:41], v[28:29], v[42:43] op_sel:[1,0,0]
	v_add_f32_dpp v36, v36, v36 quad_perm:[2,3,0,1] row_mask:0xf bank_mask:0xf bound_ctrl:1
	v_add_f32_dpp v37, v37, v37 quad_perm:[2,3,0,1] row_mask:0xf bank_mask:0xf bound_ctrl:1
	s_waitcnt lgkmcnt(0)
	v_pk_fma_f32 v[42:43], v[32:33], v[62:63], v[202:203] op_sel_hi:[0,1,1]
	v_pk_fma_f32 v[32:33], v[32:33], v[60:61], v[40:41] op_sel:[1,0,0]
	v_add_f32_dpp v36, v36, v36 row_half_mirror row_mask:0xf bank_mask:0xf bound_ctrl:1
	v_add_f32_dpp v37, v37, v37 row_half_mirror row_mask:0xf bank_mask:0xf bound_ctrl:1
	v_pk_fma_f32 v[40:41], v[34:35], v[66:67], v[42:43] op_sel_hi:[0,1,1]
	v_pk_fma_f32 v[32:33], v[34:35], v[68:69], v[32:33] op_sel:[1,0,0]
	s_and_saveexec_b64 s[20:21], s[14:15]
	ds_write_b64 v153, v[36:37] offset:49920
	s_or_b64 exec, exec, s[20:21]
	v_pk_add_f32 v[32:33], v[40:41], v[32:33]
	ds_read_b128 v[208:211], v152 offset:5376
	ds_read_b128 v[212:215], v152 offset:5392
	ds_read_b128 v[216:219], v152 offset:9472
	ds_read_b128 v[220:223], v152 offset:9488
	ds_read_b128 v[224:227], v152 offset:13568
	ds_read_b128 v[228:231], v152 offset:13584
	ds_read_b128 v[232:235], v152 offset:17664
	ds_read_b128 v[236:239], v152 offset:17680
	ds_read_b64 v[240:241], v151 offset:21760
	ds_read_b128 v[44:47], v1 offset:1280
	ds_read_b128 v[36:39], v1 offset:1296
	v_add_f32_dpp v32, v32, v32 quad_perm:[1,0,3,2] row_mask:0xf bank_mask:0xf bound_ctrl:1
	v_add_f32_dpp v33, v33, v33 quad_perm:[1,0,3,2] row_mask:0xf bank_mask:0xf bound_ctrl:1
	s_nop 0
	v_add_f32_dpp v32, v32, v32 quad_perm:[2,3,0,1] row_mask:0xf bank_mask:0xf bound_ctrl:1
	v_add_f32_dpp v33, v33, v33 quad_perm:[2,3,0,1] row_mask:0xf bank_mask:0xf bound_ctrl:1
	s_nop 0
	v_add_f32_dpp v32, v32, v32 row_half_mirror row_mask:0xf bank_mask:0xf bound_ctrl:1
	v_add_f32_dpp v33, v33, v33 row_half_mirror row_mask:0xf bank_mask:0xf bound_ctrl:1
	v_pk_mul_f32 v[34:35], v[108:109], v[32:33] op_sel_hi:[0,1]
	v_pk_fma_f32 v[34:35], v[116:117], v[132:133], v[34:35] op_sel_hi:[0,1,1] neg_lo:[0,0,1] neg_hi:[0,0,1]
	v_pk_fma_f32 v[2:3], v[2:3], v[100:101], v[34:35] op_sel_hi:[1,0,1]
	v_pk_mul_f32 v[34:35], v[108:109], v[32:33] op_sel:[1,0]
	v_pk_mul_f32 v[42:43], v[110:111], v[32:33] op_sel_hi:[0,1]
	v_pk_fma_f32 v[34:35], v[116:117], v[132:133], v[34:35] op_sel:[1,0,0] neg_lo:[0,0,1] neg_hi:[0,0,1]
	v_pk_fma_f32 v[42:43], v[118:119], v[132:133], v[42:43] op_sel_hi:[0,1,1] neg_lo:[0,0,1] neg_hi:[0,0,1]
	v_pk_fma_f32 v[40:41], v[28:29], v[100:101], v[34:35] op_sel:[0,1,0]
	v_pk_fma_f32 v[42:43], v[30:31], v[102:103], v[42:43] op_sel_hi:[1,0,1]
	v_pk_mul_f32 v[70:71], v[110:111], v[32:33] op_sel:[1,0]
	v_pk_fma_f32 v[70:71], v[118:119], v[132:133], v[70:71] op_sel:[1,0,0] neg_lo:[0,0,1] neg_hi:[0,0,1]
	v_pk_fma_f32 v[34:35], v[124:125], v[40:41], 0 op_sel:[1,0,0] op_sel_hi:[1,1,0]
	v_pk_fma_f32 v[64:65], v[64:65], v[102:103], v[70:71] op_sel:[0,1,0]
	v_pk_fma_f32 v[30:31], v[126:127], v[64:65], v[34:35] op_sel:[1,0,0]
	v_pk_mul_f32 v[34:35], v[112:113], v[32:33] op_sel_hi:[0,1]
	v_pk_fma_f32 v[34:35], v[120:121], v[132:133], v[34:35] op_sel_hi:[0,1,1] neg_lo:[0,0,1] neg_hi:[0,0,1]
	v_pk_fma_f32 v[62:63], v[62:63], v[104:105], v[34:35] op_sel_hi:[1,0,1]
	v_pk_mul_f32 v[34:35], v[112:113], v[32:33] op_sel:[1,0]
	v_pk_fma_f32 v[28:29], v[124:125], v[2:3], 0 op_sel_hi:[0,1,0]
	v_pk_fma_f32 v[34:35], v[120:121], v[132:133], v[34:35] op_sel:[1,0,0] neg_lo:[0,0,1] neg_hi:[0,0,1]
	v_pk_fma_f32 v[60:61], v[60:61], v[104:105], v[34:35] op_sel:[0,1,0]
	v_pk_mul_f32 v[34:35], v[114:115], v[32:33] op_sel_hi:[0,1]
	v_pk_fma_f32 v[34:35], v[122:123], v[132:133], v[34:35] op_sel_hi:[0,1,1] neg_lo:[0,0,1] neg_hi:[0,0,1]
	v_pk_fma_f32 v[72:73], v[66:67], v[106:107], v[34:35] op_sel_hi:[1,0,1]
	v_pk_mul_f32 v[32:33], v[114:115], v[32:33] op_sel:[1,0]
	v_pk_fma_f32 v[28:29], v[126:127], v[42:43], v[28:29] op_sel_hi:[0,1,1]
	v_pk_fma_f32 v[32:33], v[122:123], v[132:133], v[32:33] op_sel:[1,0,0] neg_lo:[0,0,1] neg_hi:[0,0,1]
	v_pk_fma_f32 v[28:29], v[128:129], v[62:63], v[28:29] op_sel_hi:[0,1,1]
	v_pk_fma_f32 v[30:31], v[128:129], v[60:61], v[30:31] op_sel:[1,0,0]
	v_pk_fma_f32 v[74:75], v[68:69], v[106:107], v[32:33] op_sel:[0,1,0]
	v_pk_fma_f32 v[28:29], v[130:131], v[72:73], v[28:29] op_sel_hi:[0,1,1]
	v_pk_fma_f32 v[30:31], v[130:131], v[74:75], v[30:31] op_sel:[1,0,0]
	v_pk_add_f32 v[28:29], v[28:29], v[30:31]
	s_waitcnt lgkmcnt(1)
	v_pk_mul_f32 v[66:67], v[46:47], v[42:43] op_sel_hi:[0,1]
	v_pk_fma_f32 v[66:67], v[44:45], v[2:3], v[66:67] op_sel_hi:[0,1,1]
	v_add_f32_dpp v28, v28, v28 quad_perm:[1,0,3,2] row_mask:0xf bank_mask:0xf bound_ctrl:1
	v_add_f32_dpp v29, v29, v29 quad_perm:[1,0,3,2] row_mask:0xf bank_mask:0xf bound_ctrl:1
	v_pk_mul_f32 v[46:47], v[46:47], v[64:65] op_sel:[1,0]
	v_pk_fma_f32 v[44:45], v[44:45], v[40:41], v[46:47] op_sel:[1,0,0]
	v_add_f32_dpp v28, v28, v28 quad_perm:[2,3,0,1] row_mask:0xf bank_mask:0xf bound_ctrl:1
	v_add_f32_dpp v29, v29, v29 quad_perm:[2,3,0,1] row_mask:0xf bank_mask:0xf bound_ctrl:1
	s_waitcnt lgkmcnt(0)
	v_pk_fma_f32 v[46:47], v[36:37], v[62:63], v[66:67] op_sel_hi:[0,1,1]
	v_pk_fma_f32 v[36:37], v[36:37], v[60:61], v[44:45] op_sel:[1,0,0]
	v_add_f32_dpp v28, v28, v28 row_half_mirror row_mask:0xf bank_mask:0xf bound_ctrl:1
	v_add_f32_dpp v29, v29, v29 row_half_mirror row_mask:0xf bank_mask:0xf bound_ctrl:1
	v_pk_fma_f32 v[44:45], v[38:39], v[72:73], v[46:47] op_sel_hi:[0,1,1]
	v_pk_fma_f32 v[36:37], v[38:39], v[74:75], v[36:37] op_sel:[1,0,0]
	s_and_saveexec_b64 s[20:21], s[14:15]
	ds_write_b64 v153, v[28:29] offset:50176
	s_or_b64 exec, exec, s[20:21]
	v_pk_add_f32 v[36:37], v[44:45], v[36:37]
	ds_read_b128 v[100:103], v152 offset:5632
	ds_read_b128 v[104:107], v152 offset:5648
	ds_read_b128 v[108:111], v152 offset:9728
	ds_read_b128 v[112:115], v152 offset:9744
	ds_read_b128 v[116:119], v152 offset:13824
	ds_read_b128 v[120:123], v152 offset:13840
	ds_read_b128 v[124:127], v152 offset:17920
	ds_read_b128 v[128:131], v152 offset:17936
	ds_read_b64 v[132:133], v151 offset:22016
	ds_read_b128 v[32:35], v1 offset:1536
	ds_read_b128 v[28:31], v1 offset:1552
	v_add_f32_dpp v36, v36, v36 quad_perm:[1,0,3,2] row_mask:0xf bank_mask:0xf bound_ctrl:1
	v_add_f32_dpp v37, v37, v37 quad_perm:[1,0,3,2] row_mask:0xf bank_mask:0xf bound_ctrl:1
	s_nop 0
	v_add_f32_dpp v36, v36, v36 quad_perm:[2,3,0,1] row_mask:0xf bank_mask:0xf bound_ctrl:1
	v_add_f32_dpp v37, v37, v37 quad_perm:[2,3,0,1] row_mask:0xf bank_mask:0xf bound_ctrl:1
	s_nop 0
	v_add_f32_dpp v36, v36, v36 row_half_mirror row_mask:0xf bank_mask:0xf bound_ctrl:1
	v_add_f32_dpp v37, v37, v37 row_half_mirror row_mask:0xf bank_mask:0xf bound_ctrl:1
	s_nop 0
	v_pk_mul_f32 v[38:39], v[216:217], v[36:37] op_sel_hi:[0,1]
	v_pk_fma_f32 v[38:39], v[224:225], v[240:241], v[38:39] op_sel_hi:[0,1,1] neg_lo:[0,0,1] neg_hi:[0,0,1]
	v_pk_fma_f32 v[70:71], v[2:3], v[208:209], v[38:39] op_sel_hi:[1,0,1]
	v_pk_mul_f32 v[2:3], v[216:217], v[36:37] op_sel:[1,0]
	s_nop 0
	v_pk_fma_f32 v[2:3], v[224:225], v[240:241], v[2:3] op_sel:[1,0,0] neg_lo:[0,0,1] neg_hi:[0,0,1]
	s_nop 0
	v_pk_fma_f32 v[68:69], v[40:41], v[208:209], v[2:3] op_sel:[0,1,0]
	v_pk_mul_f32 v[40:41], v[218:219], v[36:37] op_sel_hi:[0,1]
	v_pk_fma_f32 v[40:41], v[226:227], v[240:241], v[40:41] op_sel_hi:[0,1,1] neg_lo:[0,0,1] neg_hi:[0,0,1]
	v_pk_fma_f32 v[66:67], v[42:43], v[210:211], v[40:41] op_sel_hi:[1,0,1]
	v_pk_mul_f32 v[42:43], v[218:219], v[36:37] op_sel:[1,0]
	v_pk_fma_f32 v[42:43], v[226:227], v[240:241], v[42:43] op_sel:[1,0,0] neg_lo:[0,0,1] neg_hi:[0,0,1]
	v_pk_fma_f32 v[38:39], v[232:233], v[68:69], 0 op_sel:[1,0,0] op_sel_hi:[1,1,0]
	v_pk_fma_f32 v[64:65], v[64:65], v[210:211], v[42:43] op_sel:[0,1,0]
	v_pk_fma_f32 v[38:39], v[234:235], v[64:65], v[38:39] op_sel:[1,0,0]
	v_pk_mul_f32 v[40:41], v[220:221], v[36:37] op_sel_hi:[0,1]
	v_pk_fma_f32 v[40:41], v[228:229], v[240:241], v[40:41] op_sel_hi:[0,1,1] neg_lo:[0,0,1] neg_hi:[0,0,1]
	v_pk_fma_f32 v[62:63], v[62:63], v[212:213], v[40:41] op_sel_hi:[1,0,1]
	v_pk_mul_f32 v[40:41], v[220:221], v[36:37] op_sel:[1,0]
	v_mov_b32_e32 v42, v223
	v_pk_fma_f32 v[40:41], v[228:229], v[240:241], v[40:41] op_sel:[1,0,0] neg_lo:[0,0,1] neg_hi:[0,0,1]
	v_pk_fma_f32 v[2:3], v[232:233], v[70:71], 0 op_sel_hi:[0,1,0]
	v_pk_fma_f32 v[60:61], v[60:61], v[212:213], v[40:41] op_sel:[0,1,0]
	v_pk_mul_f32 v[40:41], v[222:223], v[36:37] op_sel_hi:[0,1]
	v_pk_fma_f32 v[40:41], v[230:231], v[240:241], v[40:41] op_sel_hi:[0,1,1] neg_lo:[0,0,1] neg_hi:[0,0,1]
	v_pk_mul_f32 v[36:37], v[42:43], v[36:37] op_sel_hi:[0,1]
	v_pk_fma_f32 v[2:3], v[234:235], v[66:67], v[2:3] op_sel_hi:[0,1,1]
	v_pk_fma_f32 v[46:47], v[72:73], v[214:215], v[40:41] op_sel_hi:[1,0,1]
	v_mov_b32_e32 v40, v215
	v_pk_fma_f32 v[36:37], v[230:231], v[240:241], v[36:37] op_sel:[1,0,0] neg_lo:[0,0,1] neg_hi:[0,0,1]
	v_pk_fma_f32 v[2:3], v[236:237], v[62:63], v[2:3] op_sel_hi:[0,1,1]
	v_pk_fma_f32 v[38:39], v[236:237], v[60:61], v[38:39] op_sel:[1,0,0]
	v_pk_fma_f32 v[44:45], v[74:75], v[40:41], v[36:37] op_sel_hi:[1,0,1]
	v_pk_fma_f32 v[2:3], v[238:239], v[46:47], v[2:3] op_sel_hi:[0,1,1]
	v_pk_fma_f32 v[36:37], v[238:239], v[44:45], v[38:39] op_sel:[1,0,0]
	v_pk_add_f32 v[2:3], v[2:3], v[36:37]
	s_nop 1
	v_add_f32_dpp v2, v2, v2 quad_perm:[1,0,3,2] row_mask:0xf bank_mask:0xf bound_ctrl:1
	v_add_f32_dpp v3, v3, v3 quad_perm:[1,0,3,2] row_mask:0xf bank_mask:0xf bound_ctrl:1
	s_nop 0
	v_add_f32_dpp v2, v2, v2 quad_perm:[2,3,0,1] row_mask:0xf bank_mask:0xf bound_ctrl:1
	v_add_f32_dpp v3, v3, v3 quad_perm:[2,3,0,1] row_mask:0xf bank_mask:0xf bound_ctrl:1
	s_nop 0
	v_add_f32_dpp v2, v2, v2 row_half_mirror row_mask:0xf bank_mask:0xf bound_ctrl:1
	v_add_f32_dpp v3, v3, v3 row_half_mirror row_mask:0xf bank_mask:0xf bound_ctrl:1
	s_and_saveexec_b64 s[20:21], s[14:15]
	ds_write_b64 v153, v[2:3] offset:50432
	s_or_b64 exec, exec, s[20:21]

.LBB0_612:
	s_andn2_saveexec_b64 s[0:1], s[0:1]
	s_cbranch_execz .LBB0_624
	v_pk_mul_f32 v[2:3], v[66:67], v[34:35] op_sel_hi:[1,0]
	v_pk_fma_f32 v[2:3], v[70:71], v[32:33], v[2:3] op_sel_hi:[1,0,1]
	v_pk_mul_f32 v[34:35], v[64:65], v[34:35] op_sel:[0,1]
	v_pk_fma_f32 v[2:3], v[62:63], v[28:29], v[2:3] op_sel_hi:[1,0,1]
	v_pk_fma_f32 v[32:33], v[68:69], v[32:33], v[34:35] op_sel:[0,1,0]
	v_pk_fma_f32 v[2:3], v[46:47], v[30:31], v[2:3] op_sel_hi:[1,0,1]
	v_pk_fma_f32 v[28:29], v[60:61], v[28:29], v[32:33] op_sel:[0,1,0]
	v_pk_fma_f32 v[28:29], v[44:45], v[30:31], v[28:29] op_sel:[0,1,0]
	s_and_b32 s20, s25, 1
	v_pk_add_f32 v[2:3], v[2:3], v[28:29]
	s_mul_i32 s21, s20, 0x6000
	s_add_i32 s21, s21, 0
	v_add_f32_dpp v2, v2, v2 quad_perm:[1,0,3,2] row_mask:0xf bank_mask:0xf bound_ctrl:1
	v_add_f32_dpp v3, v3, v3 quad_perm:[1,0,3,2] row_mask:0xf bank_mask:0xf bound_ctrl:1
	s_bitcmp1_b32 s25, 0
	v_lshl_add_u32 v152, v97, 2, s21
	v_mov_b32_dpp v28, v2 quad_perm:[2,3,0,1] row_mask:0xf bank_mask:0xf bound_ctrl:1
	v_mov_b32_dpp v29, v3 quad_perm:[2,3,0,1] row_mask:0xf bank_mask:0xf bound_ctrl:1
	v_lshl_add_u32 v1, v98, 2, s21
	s_cselect_b32 s21, 0x6000, 0
	v_pk_add_f32 v[2:3], v[2:3], v[28:29]
	v_add_u32_e32 v151, s21, v143
	ds_read_b128 v[208:211], v152 offset:5888
	ds_read_b128 v[212:215], v152 offset:5904
	ds_read_b128 v[216:219], v152 offset:9984
	ds_read_b128 v[220:223], v152 offset:10000
	ds_read_b128 v[224:227], v152 offset:14080
	ds_read_b128 v[228:231], v152 offset:14096
	ds_read_b128 v[232:235], v152 offset:18176
	ds_read_b128 v[236:239], v152 offset:18192
	ds_read_b64 v[240:241], v1 offset:22272
	ds_read_b128 v[40:43], v151 offset:1792
	ds_read_b128 v[36:39], v151 offset:1808
	v_add_f32_dpp v28, v2, v2 row_half_mirror row_mask:0xf bank_mask:0xf bound_ctrl:1
	v_add_f32_dpp v29, v3, v3 row_half_mirror row_mask:0xf bank_mask:0xf bound_ctrl:1
	s_lshl_b32 s20, s20, 12
	v_pk_mul_f32 v[2:3], v[108:109], v[28:29] op_sel_hi:[0,1]
	v_pk_fma_f32 v[2:3], v[116:117], v[132:133], v[2:3] op_sel_hi:[0,1,1] neg_lo:[0,0,1] neg_hi:[0,0,1]
	v_pk_mul_f32 v[30:31], v[108:109], v[28:29] op_sel:[1,0]
	v_pk_fma_f32 v[2:3], v[70:71], v[100:101], v[2:3] op_sel_hi:[1,0,1]
	v_pk_fma_f32 v[30:31], v[116:117], v[132:133], v[30:31] op_sel:[1,0,0] neg_lo:[0,0,1] neg_hi:[0,0,1]
	v_pk_mul_f32 v[34:35], v[110:111], v[28:29] op_sel_hi:[0,1]
	v_pk_fma_f32 v[32:33], v[68:69], v[100:101], v[30:31] op_sel:[0,1,0]
	v_pk_fma_f32 v[34:35], v[118:119], v[132:133], v[34:35] op_sel_hi:[0,1,1] neg_lo:[0,0,1] neg_hi:[0,0,1]
	v_pk_mul_f32 v[70:71], v[110:111], v[28:29] op_sel:[1,0]
	v_pk_fma_f32 v[34:35], v[66:67], v[102:103], v[34:35] op_sel_hi:[1,0,1]
	v_pk_fma_f32 v[70:71], v[118:119], v[132:133], v[70:71] op_sel:[1,0,0] neg_lo:[0,0,1] neg_hi:[0,0,1]
	v_pk_fma_f32 v[68:69], v[124:125], v[32:33], 0 op_sel:[1,0,0] op_sel_hi:[1,1,0]
	v_pk_fma_f32 v[64:65], v[64:65], v[102:103], v[70:71] op_sel:[0,1,0]
	v_pk_fma_f32 v[66:67], v[126:127], v[64:65], v[68:69] op_sel:[1,0,0]
	v_pk_mul_f32 v[68:69], v[112:113], v[28:29] op_sel_hi:[0,1]
	v_pk_fma_f32 v[68:69], v[120:121], v[132:133], v[68:69] op_sel_hi:[0,1,1] neg_lo:[0,0,1] neg_hi:[0,0,1]
	v_pk_fma_f32 v[62:63], v[62:63], v[104:105], v[68:69] op_sel_hi:[1,0,1]
	v_pk_mul_f32 v[68:69], v[112:113], v[28:29] op_sel:[1,0]
	v_pk_fma_f32 v[30:31], v[124:125], v[2:3], 0 op_sel_hi:[0,1,0]
	v_pk_fma_f32 v[68:69], v[120:121], v[132:133], v[68:69] op_sel:[1,0,0] neg_lo:[0,0,1] neg_hi:[0,0,1]
	v_pk_fma_f32 v[30:31], v[126:127], v[34:35], v[30:31] op_sel_hi:[0,1,1]
	v_pk_fma_f32 v[60:61], v[60:61], v[104:105], v[68:69] op_sel:[0,1,0]
	v_pk_fma_f32 v[70:71], v[128:129], v[60:61], v[66:67] op_sel:[1,0,0]
	v_pk_mul_f32 v[66:67], v[114:115], v[28:29] op_sel_hi:[0,1]
	v_pk_fma_f32 v[66:67], v[122:123], v[132:133], v[66:67] op_sel_hi:[0,1,1] neg_lo:[0,0,1] neg_hi:[0,0,1]
	v_pk_mul_f32 v[28:29], v[114:115], v[28:29] op_sel:[1,0]
	v_pk_fma_f32 v[30:31], v[128:129], v[62:63], v[30:31] op_sel_hi:[0,1,1]
	v_pk_fma_f32 v[66:67], v[46:47], v[106:107], v[66:67] op_sel_hi:[1,0,1]
	v_pk_fma_f32 v[28:29], v[122:123], v[132:133], v[28:29] op_sel:[1,0,0] neg_lo:[0,0,1] neg_hi:[0,0,1]
	v_pk_fma_f32 v[68:69], v[44:45], v[106:107], v[28:29] op_sel:[0,1,0]
	v_pk_fma_f32 v[28:29], v[130:131], v[66:67], v[30:31] op_sel_hi:[0,1,1]
	v_pk_fma_f32 v[30:31], v[130:131], v[68:69], v[70:71] op_sel:[1,0,0]
	v_pk_add_f32 v[28:29], v[28:29], v[30:31]
	v_add_u32_e32 v153, s20, v99
	s_nop 0
	v_add_f32_dpp v28, v28, v28 quad_perm:[1,0,3,2] row_mask:0xf bank_mask:0xf bound_ctrl:1
	v_add_f32_dpp v29, v29, v29 quad_perm:[1,0,3,2] row_mask:0xf bank_mask:0xf bound_ctrl:1
	s_nop 0
	v_add_f32_dpp v28, v28, v28 quad_perm:[2,3,0,1] row_mask:0xf bank_mask:0xf bound_ctrl:1
	v_add_f32_dpp v29, v29, v29 quad_perm:[2,3,0,1] row_mask:0xf bank_mask:0xf bound_ctrl:1
	s_nop 0
	v_add_f32_dpp v28, v28, v28 row_half_mirror row_mask:0xf bank_mask:0xf bound_ctrl:1
	v_add_f32_dpp v29, v29, v29 row_half_mirror row_mask:0xf bank_mask:0xf bound_ctrl:1
	s_and_saveexec_b64 s[20:21], s[14:15]
	ds_write_b64 v153, v[28:29] offset:50688
	s_or_b64 exec, exec, s[20:21]
	s_waitcnt lgkmcnt(1)
	v_pk_mul_f32 v[202:203], v[42:43], v[34:35] op_sel_hi:[0,1]
	v_pk_fma_f32 v[202:203], v[40:41], v[2:3], v[202:203] op_sel_hi:[0,1,1]
	v_pk_mul_f32 v[42:43], v[42:43], v[64:65] op_sel:[1,0]
	v_pk_fma_f32 v[40:41], v[40:41], v[32:33], v[42:43] op_sel:[1,0,0]
	s_waitcnt lgkmcnt(0)
	v_pk_fma_f32 v[42:43], v[36:37], v[62:63], v[202:203] op_sel_hi:[0,1,1]
	v_pk_fma_f32 v[36:37], v[36:37], v[60:61], v[40:41] op_sel:[1,0,0]
	v_pk_fma_f32 v[40:41], v[38:39], v[66:67], v[42:43] op_sel_hi:[0,1,1]
	v_pk_fma_f32 v[36:37], v[38:39], v[68:69], v[36:37] op_sel:[1,0,0]
	v_pk_add_f32 v[36:37], v[40:41], v[36:37]
	ds_read_b128 v[100:103], v152 offset:6144
	ds_read_b128 v[104:107], v152 offset:6160
	ds_read_b128 v[108:111], v152 offset:10240
	ds_read_b128 v[112:115], v152 offset:10256
	ds_read_b128 v[116:119], v152 offset:14336
	ds_read_b128 v[120:123], v152 offset:14352
	ds_read_b128 v[124:127], v152 offset:18432
	ds_read_b128 v[128:131], v152 offset:18448
	ds_read_b64 v[132:133], v1 offset:22528
	ds_read_b128 v[44:47], v151 offset:2048
	ds_read_b128 v[28:31], v151 offset:2064
	v_add_f32_dpp v36, v36, v36 quad_perm:[1,0,3,2] row_mask:0xf bank_mask:0xf bound_ctrl:1
	v_add_f32_dpp v37, v37, v37 quad_perm:[1,0,3,2] row_mask:0xf bank_mask:0xf bound_ctrl:1
	s_nop 0
	v_add_f32_dpp v36, v36, v36 quad_perm:[2,3,0,1] row_mask:0xf bank_mask:0xf bound_ctrl:1
	v_add_f32_dpp v37, v37, v37 quad_perm:[2,3,0,1] row_mask:0xf bank_mask:0xf bound_ctrl:1
	s_nop 0
	v_add_f32_dpp v40, v36, v36 row_half_mirror row_mask:0xf bank_mask:0xf bound_ctrl:1
	v_add_f32_dpp v41, v37, v37 row_half_mirror row_mask:0xf bank_mask:0xf bound_ctrl:1
	v_pk_mul_f32 v[36:37], v[216:217], v[40:41] op_sel_hi:[0,1]
	v_pk_fma_f32 v[36:37], v[224:225], v[240:241], v[36:37] op_sel_hi:[0,1,1] neg_lo:[0,0,1] neg_hi:[0,0,1]
	v_pk_fma_f32 v[2:3], v[2:3], v[208:209], v[36:37] op_sel_hi:[1,0,1]
	v_pk_mul_f32 v[36:37], v[216:217], v[40:41] op_sel:[1,0]
	v_pk_mul_f32 v[38:39], v[218:219], v[40:41] op_sel_hi:[0,1]
	v_pk_fma_f32 v[36:37], v[224:225], v[240:241], v[36:37] op_sel:[1,0,0] neg_lo:[0,0,1] neg_hi:[0,0,1]
	v_pk_fma_f32 v[38:39], v[226:227], v[240:241], v[38:39] op_sel_hi:[0,1,1] neg_lo:[0,0,1] neg_hi:[0,0,1]
	v_pk_fma_f32 v[36:37], v[32:33], v[208:209], v[36:37] op_sel:[0,1,0]
	v_pk_fma_f32 v[38:39], v[34:35], v[210:211], v[38:39] op_sel_hi:[1,0,1]
	v_pk_mul_f32 v[70:71], v[218:219], v[40:41] op_sel:[1,0]
	v_pk_fma_f32 v[70:71], v[226:227], v[240:241], v[70:71] op_sel:[1,0,0] neg_lo:[0,0,1] neg_hi:[0,0,1]
	v_pk_fma_f32 v[42:43], v[232:233], v[36:37], 0 op_sel:[1,0,0] op_sel_hi:[1,1,0]
	v_pk_fma_f32 v[64:65], v[64:65], v[210:211], v[70:71] op_sel:[0,1,0]
	v_pk_fma_f32 v[34:35], v[234:235], v[64:65], v[42:43] op_sel:[1,0,0]
	v_pk_mul_f32 v[42:43], v[220:221], v[40:41] op_sel_hi:[0,1]
	v_pk_fma_f32 v[42:43], v[228:229], v[240:241], v[42:43] op_sel_hi:[0,1,1] neg_lo:[0,0,1] neg_hi:[0,0,1]
	v_pk_fma_f32 v[62:63], v[62:63], v[212:213], v[42:43] op_sel_hi:[1,0,1]
	v_pk_mul_f32 v[42:43], v[220:221], v[40:41] op_sel:[1,0]
	v_pk_fma_f32 v[42:43], v[228:229], v[240:241], v[42:43] op_sel:[1,0,0] neg_lo:[0,0,1] neg_hi:[0,0,1]
	v_pk_fma_f32 v[32:33], v[232:233], v[2:3], 0 op_sel_hi:[0,1,0]
	v_pk_fma_f32 v[60:61], v[60:61], v[212:213], v[42:43] op_sel:[0,1,0]
	v_pk_mul_f32 v[42:43], v[222:223], v[40:41] op_sel_hi:[0,1]
	v_pk_fma_f32 v[42:43], v[230:231], v[240:241], v[42:43] op_sel_hi:[0,1,1] neg_lo:[0,0,1] neg_hi:[0,0,1]
	v_pk_mul_f32 v[40:41], v[222:223], v[40:41] op_sel:[1,0]
	v_pk_fma_f32 v[32:33], v[234:235], v[38:39], v[32:33] op_sel_hi:[0,1,1]
	v_pk_fma_f32 v[66:67], v[66:67], v[214:215], v[42:43] op_sel_hi:[1,0,1]
	v_pk_fma_f32 v[40:41], v[230:231], v[240:241], v[40:41] op_sel:[1,0,0] neg_lo:[0,0,1] neg_hi:[0,0,1]
	v_pk_fma_f32 v[32:33], v[236:237], v[62:63], v[32:33] op_sel_hi:[0,1,1]
	v_pk_fma_f32 v[34:35], v[236:237], v[60:61], v[34:35] op_sel:[1,0,0]
	v_pk_fma_f32 v[68:69], v[68:69], v[214:215], v[40:41] op_sel:[0,1,0]
	v_pk_fma_f32 v[32:33], v[238:239], v[66:67], v[32:33] op_sel_hi:[0,1,1]
	v_pk_fma_f32 v[34:35], v[238:239], v[68:69], v[34:35] op_sel:[1,0,0]
	v_pk_add_f32 v[32:33], v[32:33], v[34:35]
	s_waitcnt lgkmcnt(1)
	v_pk_mul_f32 v[202:203], v[46:47], v[38:39] op_sel_hi:[0,1]
	v_pk_fma_f32 v[202:203], v[44:45], v[2:3], v[202:203] op_sel_hi:[0,1,1]
	v_add_f32_dpp v32, v32, v32 quad_perm:[1,0,3,2] row_mask:0xf bank_mask:0xf bound_ctrl:1
	v_add_f32_dpp v33, v33, v33 quad_perm:[1,0,3,2] row_mask:0xf bank_mask:0xf bound_ctrl:1
	v_pk_mul_f32 v[46:47], v[46:47], v[64:65] op_sel:[1,0]
	v_pk_fma_f32 v[44:45], v[44:45], v[36:37], v[46:47] op_sel:[1,0,0]
	v_add_f32_dpp v32, v32, v32 quad_perm:[2,3,0,1] row_mask:0xf bank_mask:0xf bound_ctrl:1
	v_add_f32_dpp v33, v33, v33 quad_perm:[2,3,0,1] row_mask:0xf bank_mask:0xf bound_ctrl:1
	s_waitcnt lgkmcnt(0)
	v_pk_fma_f32 v[46:47], v[28:29], v[62:63], v[202:203] op_sel_hi:[0,1,1]
	v_pk_fma_f32 v[28:29], v[28:29], v[60:61], v[44:45] op_sel:[1,0,0]
	v_add_f32_dpp v32, v32, v32 row_half_mirror row_mask:0xf bank_mask:0xf bound_ctrl:1
	v_add_f32_dpp v33, v33, v33 row_half_mirror row_mask:0xf bank_mask:0xf bound_ctrl:1
	v_pk_fma_f32 v[44:45], v[30:31], v[66:67], v[46:47] op_sel_hi:[0,1,1]
	v_pk_fma_f32 v[28:29], v[30:31], v[68:69], v[28:29] op_sel:[1,0,0]
	s_and_saveexec_b64 s[20:21], s[14:15]
	ds_write_b64 v153, v[32:33] offset:50944
	s_or_b64 exec, exec, s[20:21]
	v_pk_add_f32 v[28:29], v[44:45], v[28:29]
	ds_read_b128 v[208:211], v152 offset:6400
	ds_read_b128 v[212:215], v152 offset:6416
	ds_read_b128 v[216:219], v152 offset:10496
	ds_read_b128 v[220:223], v152 offset:10512
	ds_read_b128 v[224:227], v152 offset:14592
	ds_read_b128 v[228:231], v152 offset:14608
	ds_read_b128 v[232:235], v152 offset:18688
	ds_read_b128 v[236:239], v152 offset:18704
	ds_read_b64 v[240:241], v1 offset:22784
	ds_read_b128 v[40:43], v151 offset:2304
	ds_read_b128 v[32:35], v151 offset:2320
	v_add_f32_dpp v28, v28, v28 quad_perm:[1,0,3,2] row_mask:0xf bank_mask:0xf bound_ctrl:1
	v_add_f32_dpp v29, v29, v29 quad_perm:[1,0,3,2] row_mask:0xf bank_mask:0xf bound_ctrl:1
	s_nop 0
	v_add_f32_dpp v28, v28, v28 quad_perm:[2,3,0,1] row_mask:0xf bank_mask:0xf bound_ctrl:1
	v_add_f32_dpp v29, v29, v29 quad_perm:[2,3,0,1] row_mask:0xf bank_mask:0xf bound_ctrl:1
	s_nop 0
	v_add_f32_dpp v44, v28, v28 row_half_mirror row_mask:0xf bank_mask:0xf bound_ctrl:1
	v_add_f32_dpp v45, v29, v29 row_half_mirror row_mask:0xf bank_mask:0xf bound_ctrl:1
	v_pk_mul_f32 v[28:29], v[108:109], v[44:45] op_sel_hi:[0,1]
	v_pk_fma_f32 v[28:29], v[116:117], v[132:133], v[28:29] op_sel_hi:[0,1,1] neg_lo:[0,0,1] neg_hi:[0,0,1]
	v_pk_fma_f32 v[2:3], v[2:3], v[100:101], v[28:29] op_sel_hi:[1,0,1]
	v_pk_mul_f32 v[28:29], v[108:109], v[44:45] op_sel:[1,0]
	v_pk_mul_f32 v[30:31], v[110:111], v[44:45] op_sel_hi:[0,1]
	v_pk_fma_f32 v[28:29], v[116:117], v[132:133], v[28:29] op_sel:[1,0,0] neg_lo:[0,0,1] neg_hi:[0,0,1]
	v_pk_fma_f32 v[30:31], v[118:119], v[132:133], v[30:31] op_sel_hi:[0,1,1] neg_lo:[0,0,1] neg_hi:[0,0,1]
	v_pk_fma_f32 v[28:29], v[36:37], v[100:101], v[28:29] op_sel:[0,1,0]
	v_pk_fma_f32 v[30:31], v[38:39], v[102:103], v[30:31] op_sel_hi:[1,0,1]
	v_pk_mul_f32 v[70:71], v[110:111], v[44:45] op_sel:[1,0]
	v_pk_fma_f32 v[70:71], v[118:119], v[132:133], v[70:71] op_sel:[1,0,0] neg_lo:[0,0,1] neg_hi:[0,0,1]
	v_pk_fma_f32 v[46:47], v[124:125], v[28:29], 0 op_sel:[1,0,0] op_sel_hi:[1,1,0]
	v_pk_fma_f32 v[64:65], v[64:65], v[102:103], v[70:71] op_sel:[0,1,0]
	v_pk_fma_f32 v[38:39], v[126:127], v[64:65], v[46:47] op_sel:[1,0,0]
	v_pk_mul_f32 v[46:47], v[112:113], v[44:45] op_sel_hi:[0,1]
	v_pk_fma_f32 v[46:47], v[120:121], v[132:133], v[46:47] op_sel_hi:[0,1,1] neg_lo:[0,0,1] neg_hi:[0,0,1]
	v_pk_fma_f32 v[62:63], v[62:63], v[104:105], v[46:47] op_sel_hi:[1,0,1]
	v_pk_mul_f32 v[46:47], v[112:113], v[44:45] op_sel:[1,0]
	v_pk_fma_f32 v[46:47], v[120:121], v[132:133], v[46:47] op_sel:[1,0,0] neg_lo:[0,0,1] neg_hi:[0,0,1]
	v_pk_fma_f32 v[36:37], v[124:125], v[2:3], 0 op_sel_hi:[0,1,0]
	v_pk_fma_f32 v[60:61], v[60:61], v[104:105], v[46:47] op_sel:[0,1,0]
	v_pk_mul_f32 v[46:47], v[114:115], v[44:45] op_sel_hi:[0,1]
	v_pk_fma_f32 v[46:47], v[122:123], v[132:133], v[46:47] op_sel_hi:[0,1,1] neg_lo:[0,0,1] neg_hi:[0,0,1]
	v_pk_mul_f32 v[44:45], v[114:115], v[44:45] op_sel:[1,0]
	v_pk_fma_f32 v[36:37], v[126:127], v[30:31], v[36:37] op_sel_hi:[0,1,1]
	v_pk_fma_f32 v[66:67], v[66:67], v[106:107], v[46:47] op_sel_hi:[1,0,1]
	v_pk_fma_f32 v[44:45], v[122:123], v[132:133], v[44:45] op_sel:[1,0,0] neg_lo:[0,0,1] neg_hi:[0,0,1]
	v_pk_fma_f32 v[36:37], v[128:129], v[62:63], v[36:37] op_sel_hi:[0,1,1]
	v_pk_fma_f32 v[38:39], v[128:129], v[60:61], v[38:39] op_sel:[1,0,0]
	v_pk_fma_f32 v[68:69], v[68:69], v[106:107], v[44:45] op_sel:[0,1,0]
	v_pk_fma_f32 v[36:37], v[130:131], v[66:67], v[36:37] op_sel_hi:[0,1,1]
	v_pk_fma_f32 v[38:39], v[130:131], v[68:69], v[38:39] op_sel:[1,0,0]
	v_pk_add_f32 v[36:37], v[36:37], v[38:39]
	s_waitcnt lgkmcnt(1)
	v_pk_mul_f32 v[202:203], v[42:43], v[30:31] op_sel_hi:[0,1]
	v_pk_fma_f32 v[202:203], v[40:41], v[2:3], v[202:203] op_sel_hi:[0,1,1]
	v_add_f32_dpp v36, v36, v36 quad_perm:[1,0,3,2] row_mask:0xf bank_mask:0xf bound_ctrl:1
	v_add_f32_dpp v37, v37, v37 quad_perm:[1,0,3,2] row_mask:0xf bank_mask:0xf bound_ctrl:1
	v_pk_mul_f32 v[42:43], v[42:43], v[64:65] op_sel:[1,0]
	v_pk_fma_f32 v[40:41], v[40:41], v[28:29], v[42:43] op_sel:[1,0,0]
	v_add_f32_dpp v36, v36, v36 quad_perm:[2,3,0,1] row_mask:0xf bank_mask:0xf bound_ctrl:1
	v_add_f32_dpp v37, v37, v37 quad_perm:[2,3,0,1] row_mask:0xf bank_mask:0xf bound_ctrl:1
	s_waitcnt lgkmcnt(0)
	v_pk_fma_f32 v[42:43], v[32:33], v[62:63], v[202:203] op_sel_hi:[0,1,1]
	v_pk_fma_f32 v[32:33], v[32:33], v[60:61], v[40:41] op_sel:[1,0,0]
	v_add_f32_dpp v36, v36, v36 row_half_mirror row_mask:0xf bank_mask:0xf bound_ctrl:1
	v_add_f32_dpp v37, v37, v37 row_half_mirror row_mask:0xf bank_mask:0xf bound_ctrl:1
	v_pk_fma_f32 v[40:41], v[34:35], v[66:67], v[42:43] op_sel_hi:[0,1,1]
	v_pk_fma_f32 v[32:33], v[34:35], v[68:69], v[32:33] op_sel:[1,0,0]
	s_and_saveexec_b64 s[20:21], s[14:15]
	ds_write_b64 v153, v[36:37] offset:51200
	s_or_b64 exec, exec, s[20:21]
	v_pk_add_f32 v[32:33], v[40:41], v[32:33]
	ds_read_b128 v[100:103], v152 offset:6656
	ds_read_b128 v[104:107], v152 offset:6672
	ds_read_b128 v[108:111], v152 offset:10752
	ds_read_b128 v[112:115], v152 offset:10768
	ds_read_b128 v[116:119], v152 offset:14848
	ds_read_b128 v[120:123], v152 offset:14864
	ds_read_b128 v[124:127], v152 offset:18944
	ds_read_b128 v[128:131], v152 offset:18960
	ds_read_b64 v[132:133], v1 offset:23040
	ds_read_b128 v[44:47], v151 offset:2560
	ds_read_b128 v[36:39], v151 offset:2576
	v_add_f32_dpp v32, v32, v32 quad_perm:[1,0,3,2] row_mask:0xf bank_mask:0xf bound_ctrl:1
	v_add_f32_dpp v33, v33, v33 quad_perm:[1,0,3,2] row_mask:0xf bank_mask:0xf bound_ctrl:1
	s_nop 0
	v_add_f32_dpp v32, v32, v32 quad_perm:[2,3,0,1] row_mask:0xf bank_mask:0xf bound_ctrl:1
	v_add_f32_dpp v33, v33, v33 quad_perm:[2,3,0,1] row_mask:0xf bank_mask:0xf bound_ctrl:1
	s_nop 0
	v_add_f32_dpp v32, v32, v32 row_half_mirror row_mask:0xf bank_mask:0xf bound_ctrl:1
	v_add_f32_dpp v33, v33, v33 row_half_mirror row_mask:0xf bank_mask:0xf bound_ctrl:1
	v_pk_mul_f32 v[34:35], v[216:217], v[32:33] op_sel_hi:[0,1]
	v_pk_fma_f32 v[34:35], v[224:225], v[240:241], v[34:35] op_sel_hi:[0,1,1] neg_lo:[0,0,1] neg_hi:[0,0,1]
	v_pk_fma_f32 v[2:3], v[2:3], v[208:209], v[34:35] op_sel_hi:[1,0,1]
	v_pk_mul_f32 v[34:35], v[216:217], v[32:33] op_sel:[1,0]
	v_pk_mul_f32 v[42:43], v[218:219], v[32:33] op_sel_hi:[0,1]
	v_pk_fma_f32 v[34:35], v[224:225], v[240:241], v[34:35] op_sel:[1,0,0] neg_lo:[0,0,1] neg_hi:[0,0,1]
	v_pk_fma_f32 v[42:43], v[226:227], v[240:241], v[42:43] op_sel_hi:[0,1,1] neg_lo:[0,0,1] neg_hi:[0,0,1]
	v_pk_fma_f32 v[40:41], v[28:29], v[208:209], v[34:35] op_sel:[0,1,0]
	v_pk_fma_f32 v[42:43], v[30:31], v[210:211], v[42:43] op_sel_hi:[1,0,1]
	v_pk_mul_f32 v[70:71], v[218:219], v[32:33] op_sel:[1,0]
	v_pk_fma_f32 v[70:71], v[226:227], v[240:241], v[70:71] op_sel:[1,0,0] neg_lo:[0,0,1] neg_hi:[0,0,1]
	v_pk_fma_f32 v[34:35], v[232:233], v[40:41], 0 op_sel:[1,0,0] op_sel_hi:[1,1,0]
	v_pk_fma_f32 v[64:65], v[64:65], v[210:211], v[70:71] op_sel:[0,1,0]
	v_pk_fma_f32 v[30:31], v[234:235], v[64:65], v[34:35] op_sel:[1,0,0]
	v_pk_mul_f32 v[34:35], v[220:221], v[32:33] op_sel_hi:[0,1]
	v_pk_fma_f32 v[34:35], v[228:229], v[240:241], v[34:35] op_sel_hi:[0,1,1] neg_lo:[0,0,1] neg_hi:[0,0,1]
	v_pk_fma_f32 v[62:63], v[62:63], v[212:213], v[34:35] op_sel_hi:[1,0,1]
	v_pk_mul_f32 v[34:35], v[220:221], v[32:33] op_sel:[1,0]
	v_pk_fma_f32 v[28:29], v[232:233], v[2:3], 0 op_sel_hi:[0,1,0]
	v_pk_fma_f32 v[34:35], v[228:229], v[240:241], v[34:35] op_sel:[1,0,0] neg_lo:[0,0,1] neg_hi:[0,0,1]
	v_pk_fma_f32 v[60:61], v[60:61], v[212:213], v[34:35] op_sel:[0,1,0]
	v_pk_mul_f32 v[34:35], v[222:223], v[32:33] op_sel_hi:[0,1]
	v_pk_fma_f32 v[34:35], v[230:231], v[240:241], v[34:35] op_sel_hi:[0,1,1] neg_lo:[0,0,1] neg_hi:[0,0,1]
	v_pk_fma_f32 v[72:73], v[66:67], v[214:215], v[34:35] op_sel_hi:[1,0,1]
	v_pk_mul_f32 v[32:33], v[222:223], v[32:33] op_sel:[1,0]
	v_pk_fma_f32 v[28:29], v[234:235], v[42:43], v[28:29] op_sel_hi:[0,1,1]
	v_pk_fma_f32 v[32:33], v[230:231], v[240:241], v[32:33] op_sel:[1,0,0] neg_lo:[0,0,1] neg_hi:[0,0,1]
	v_pk_fma_f32 v[28:29], v[236:237], v[62:63], v[28:29] op_sel_hi:[0,1,1]
	v_pk_fma_f32 v[30:31], v[236:237], v[60:61], v[30:31] op_sel:[1,0,0]
	v_pk_fma_f32 v[74:75], v[68:69], v[214:215], v[32:33] op_sel:[0,1,0]
	v_pk_fma_f32 v[28:29], v[238:239], v[72:73], v[28:29] op_sel_hi:[0,1,1]
	v_pk_fma_f32 v[30:31], v[238:239], v[74:75], v[30:31] op_sel:[1,0,0]
	v_pk_add_f32 v[28:29], v[28:29], v[30:31]
	s_waitcnt lgkmcnt(1)
	v_pk_mul_f32 v[66:67], v[46:47], v[42:43] op_sel_hi:[0,1]
	v_pk_fma_f32 v[66:67], v[44:45], v[2:3], v[66:67] op_sel_hi:[0,1,1]
	v_add_f32_dpp v28, v28, v28 quad_perm:[1,0,3,2] row_mask:0xf bank_mask:0xf bound_ctrl:1
	v_add_f32_dpp v29, v29, v29 quad_perm:[1,0,3,2] row_mask:0xf bank_mask:0xf bound_ctrl:1
	v_pk_mul_f32 v[46:47], v[46:47], v[64:65] op_sel:[1,0]
	v_pk_fma_f32 v[44:45], v[44:45], v[40:41], v[46:47] op_sel:[1,0,0]
	v_add_f32_dpp v28, v28, v28 quad_perm:[2,3,0,1] row_mask:0xf bank_mask:0xf bound_ctrl:1
	v_add_f32_dpp v29, v29, v29 quad_perm:[2,3,0,1] row_mask:0xf bank_mask:0xf bound_ctrl:1
	s_waitcnt lgkmcnt(0)
	v_pk_fma_f32 v[46:47], v[36:37], v[62:63], v[66:67] op_sel_hi:[0,1,1]
	v_pk_fma_f32 v[36:37], v[36:37], v[60:61], v[44:45] op_sel:[1,0,0]
	v_add_f32_dpp v28, v28, v28 row_half_mirror row_mask:0xf bank_mask:0xf bound_ctrl:1
	v_add_f32_dpp v29, v29, v29 row_half_mirror row_mask:0xf bank_mask:0xf bound_ctrl:1
	v_pk_fma_f32 v[44:45], v[38:39], v[72:73], v[46:47] op_sel_hi:[0,1,1]
	v_pk_fma_f32 v[36:37], v[38:39], v[74:75], v[36:37] op_sel:[1,0,0]
	s_and_saveexec_b64 s[20:21], s[14:15]
	ds_write_b64 v153, v[28:29] offset:51456
	s_or_b64 exec, exec, s[20:21]
	v_pk_add_f32 v[36:37], v[44:45], v[36:37]
	ds_read_b128 v[208:211], v152 offset:6912
	ds_read_b128 v[212:215], v152 offset:6928
	ds_read_b128 v[216:219], v152 offset:11008
	ds_read_b128 v[220:223], v152 offset:11024
	ds_read_b128 v[224:227], v152 offset:15104
	ds_read_b128 v[228:231], v152 offset:15120
	ds_read_b128 v[232:235], v152 offset:19200
	ds_read_b128 v[236:239], v152 offset:19216
	ds_read_b64 v[240:241], v1 offset:23296
	ds_read_b128 v[32:35], v151 offset:2816
	ds_read_b128 v[28:31], v151 offset:2832
	v_add_f32_dpp v36, v36, v36 quad_perm:[1,0,3,2] row_mask:0xf bank_mask:0xf bound_ctrl:1
	v_add_f32_dpp v37, v37, v37 quad_perm:[1,0,3,2] row_mask:0xf bank_mask:0xf bound_ctrl:1
	s_nop 0
	v_add_f32_dpp v36, v36, v36 quad_perm:[2,3,0,1] row_mask:0xf bank_mask:0xf bound_ctrl:1
	v_add_f32_dpp v37, v37, v37 quad_perm:[2,3,0,1] row_mask:0xf bank_mask:0xf bound_ctrl:1
	s_nop 0
	v_add_f32_dpp v36, v36, v36 row_half_mirror row_mask:0xf bank_mask:0xf bound_ctrl:1
	v_add_f32_dpp v37, v37, v37 row_half_mirror row_mask:0xf bank_mask:0xf bound_ctrl:1
	s_nop 0
	v_pk_mul_f32 v[38:39], v[108:109], v[36:37] op_sel_hi:[0,1]
	v_pk_fma_f32 v[38:39], v[116:117], v[132:133], v[38:39] op_sel_hi:[0,1,1] neg_lo:[0,0,1] neg_hi:[0,0,1]
	v_pk_fma_f32 v[70:71], v[2:3], v[100:101], v[38:39] op_sel_hi:[1,0,1]
	v_pk_mul_f32 v[2:3], v[108:109], v[36:37] op_sel:[1,0]
	s_nop 0
	v_pk_fma_f32 v[2:3], v[116:117], v[132:133], v[2:3] op_sel:[1,0,0] neg_lo:[0,0,1] neg_hi:[0,0,1]
	s_nop 0
	v_pk_fma_f32 v[68:69], v[40:41], v[100:101], v[2:3] op_sel:[0,1,0]
	v_pk_mul_f32 v[40:41], v[110:111], v[36:37] op_sel_hi:[0,1]
	v_pk_fma_f32 v[40:41], v[118:119], v[132:133], v[40:41] op_sel_hi:[0,1,1] neg_lo:[0,0,1] neg_hi:[0,0,1]
	v_pk_fma_f32 v[66:67], v[42:43], v[102:103], v[40:41] op_sel_hi:[1,0,1]
	v_pk_mul_f32 v[42:43], v[110:111], v[36:37] op_sel:[1,0]
	v_pk_fma_f32 v[42:43], v[118:119], v[132:133], v[42:43] op_sel:[1,0,0] neg_lo:[0,0,1] neg_hi:[0,0,1]
	v_pk_fma_f32 v[38:39], v[124:125], v[68:69], 0 op_sel:[1,0,0] op_sel_hi:[1,1,0]
	v_pk_fma_f32 v[64:65], v[64:65], v[102:103], v[42:43] op_sel:[0,1,0]
	v_pk_fma_f32 v[38:39], v[126:127], v[64:65], v[38:39] op_sel:[1,0,0]
	v_pk_mul_f32 v[40:41], v[112:113], v[36:37] op_sel_hi:[0,1]
	v_pk_fma_f32 v[40:41], v[120:121], v[132:133], v[40:41] op_sel_hi:[0,1,1] neg_lo:[0,0,1] neg_hi:[0,0,1]
	v_pk_fma_f32 v[62:63], v[62:63], v[104:105], v[40:41] op_sel_hi:[1,0,1]
	v_pk_mul_f32 v[40:41], v[112:113], v[36:37] op_sel:[1,0]
	v_mov_b32_e32 v42, v115
	v_pk_fma_f32 v[40:41], v[120:121], v[132:133], v[40:41] op_sel:[1,0,0] neg_lo:[0,0,1] neg_hi:[0,0,1]
	v_pk_fma_f32 v[2:3], v[124:125], v[70:71], 0 op_sel_hi:[0,1,0]
	v_pk_fma_f32 v[60:61], v[60:61], v[104:105], v[40:41] op_sel:[0,1,0]
	v_pk_mul_f32 v[40:41], v[114:115], v[36:37] op_sel_hi:[0,1]
	v_pk_fma_f32 v[40:41], v[122:123], v[132:133], v[40:41] op_sel_hi:[0,1,1] neg_lo:[0,0,1] neg_hi:[0,0,1]
	v_pk_mul_f32 v[36:37], v[42:43], v[36:37] op_sel_hi:[0,1]
	v_pk_fma_f32 v[2:3], v[126:127], v[66:67], v[2:3] op_sel_hi:[0,1,1]
	v_pk_fma_f32 v[46:47], v[72:73], v[106:107], v[40:41] op_sel_hi:[1,0,1]
	v_mov_b32_e32 v40, v107
	v_pk_fma_f32 v[36:37], v[122:123], v[132:133], v[36:37] op_sel:[1,0,0] neg_lo:[0,0,1] neg_hi:[0,0,1]
	v_pk_fma_f32 v[2:3], v[128:129], v[62:63], v[2:3] op_sel_hi:[0,1,1]
	v_pk_fma_f32 v[38:39], v[128:129], v[60:61], v[38:39] op_sel:[1,0,0]
	v_pk_fma_f32 v[44:45], v[74:75], v[40:41], v[36:37] op_sel_hi:[1,0,1]
	v_pk_fma_f32 v[2:3], v[130:131], v[46:47], v[2:3] op_sel_hi:[0,1,1]
	v_pk_fma_f32 v[36:37], v[130:131], v[44:45], v[38:39] op_sel:[1,0,0]
	v_pk_add_f32 v[2:3], v[2:3], v[36:37]
	s_nop 1
	v_add_f32_dpp v2, v2, v2 quad_perm:[1,0,3,2] row_mask:0xf bank_mask:0xf bound_ctrl:1
	v_add_f32_dpp v3, v3, v3 quad_perm:[1,0,3,2] row_mask:0xf bank_mask:0xf bound_ctrl:1
	s_nop 0
	v_add_f32_dpp v2, v2, v2 quad_perm:[2,3,0,1] row_mask:0xf bank_mask:0xf bound_ctrl:1
	v_add_f32_dpp v3, v3, v3 quad_perm:[2,3,0,1] row_mask:0xf bank_mask:0xf bound_ctrl:1
	s_nop 0
	v_add_f32_dpp v2, v2, v2 row_half_mirror row_mask:0xf bank_mask:0xf bound_ctrl:1
	v_add_f32_dpp v3, v3, v3 row_half_mirror row_mask:0xf bank_mask:0xf bound_ctrl:1
	s_and_saveexec_b64 s[20:21], s[14:15]
	ds_write_b64 v153, v[2:3] offset:51712
	s_or_b64 exec, exec, s[20:21]

.LBB0_635:
	s_andn2_saveexec_b64 s[0:1], s[0:1]
	s_cbranch_execz .LBB0_576
	v_pk_mul_f32 v[2:3], v[66:67], v[34:35] op_sel_hi:[1,0]
	v_pk_fma_f32 v[2:3], v[70:71], v[32:33], v[2:3] op_sel_hi:[1,0,1]
	v_pk_mul_f32 v[34:35], v[64:65], v[34:35] op_sel:[0,1]
	v_pk_fma_f32 v[2:3], v[62:63], v[28:29], v[2:3] op_sel_hi:[1,0,1]
	v_pk_fma_f32 v[32:33], v[68:69], v[32:33], v[34:35] op_sel:[0,1,0]
	v_pk_fma_f32 v[2:3], v[46:47], v[30:31], v[2:3] op_sel_hi:[1,0,1]
	v_pk_fma_f32 v[28:29], v[60:61], v[28:29], v[32:33] op_sel:[0,1,0]
	v_pk_fma_f32 v[28:29], v[44:45], v[30:31], v[28:29] op_sel:[0,1,0]
	s_and_b32 s20, s25, 1
	v_pk_add_f32 v[2:3], v[2:3], v[28:29]
	s_mul_i32 s21, s20, 0x6000
	s_add_i32 s21, s21, 0
	v_add_f32_dpp v2, v2, v2 quad_perm:[1,0,3,2] row_mask:0xf bank_mask:0xf bound_ctrl:1
	v_add_f32_dpp v3, v3, v3 quad_perm:[1,0,3,2] row_mask:0xf bank_mask:0xf bound_ctrl:1
	s_lshl_b32 s22, s20, 12
	s_nop 0
	s_cmp_eq_u32 s20, 1
	v_lshl_add_u32 v1, v97, 2, s21
	v_add_f32_dpp v2, v2, v2 quad_perm:[2,3,0,1] row_mask:0xf bank_mask:0xf bound_ctrl:1
	v_add_f32_dpp v3, v3, v3 quad_perm:[2,3,0,1] row_mask:0xf bank_mask:0xf bound_ctrl:1
	s_cselect_b32 s20, 0x6000, 0
	s_nop 0
	v_lshl_add_u32 v73, v98, 2, s21
	v_add_u32_e32 v74, s20, v143
	ds_read_b128 v[100:103], v1 offset:7168
	ds_read_b128 v[104:107], v1 offset:7184
	ds_read_b128 v[108:111], v1 offset:11264
	ds_read_b128 v[112:115], v1 offset:11280
	ds_read_b128 v[116:119], v1 offset:15360
	ds_read_b128 v[120:123], v1 offset:15376
	ds_read_b128 v[124:127], v1 offset:19456
	ds_read_b128 v[128:131], v1 offset:19472
	ds_read_b64 v[132:133], v73 offset:23552
	ds_read_b128 v[40:43], v74 offset:3072
	ds_read_b128 v[36:39], v74 offset:3088
	v_add_f32_dpp v28, v2, v2 row_half_mirror row_mask:0xf bank_mask:0xf bound_ctrl:1
	v_add_f32_dpp v29, v3, v3 row_half_mirror row_mask:0xf bank_mask:0xf bound_ctrl:1
	v_pk_mul_f32 v[2:3], v[216:217], v[28:29] op_sel_hi:[0,1]
	v_pk_fma_f32 v[2:3], v[224:225], v[240:241], v[2:3] op_sel_hi:[0,1,1] neg_lo:[0,0,1] neg_hi:[0,0,1]
	v_pk_fma_f32 v[2:3], v[70:71], v[208:209], v[2:3] op_sel_hi:[1,0,1]
	v_pk_mul_f32 v[30:31], v[216:217], v[28:29] op_sel:[1,0]
	v_pk_mul_f32 v[34:35], v[218:219], v[28:29] op_sel_hi:[0,1]
	v_pk_fma_f32 v[30:31], v[224:225], v[240:241], v[30:31] op_sel:[1,0,0] neg_lo:[0,0,1] neg_hi:[0,0,1]
	v_pk_fma_f32 v[34:35], v[226:227], v[240:241], v[34:35] op_sel_hi:[0,1,1] neg_lo:[0,0,1] neg_hi:[0,0,1]
	v_pk_mul_f32 v[70:71], v[218:219], v[28:29] op_sel:[1,0]
	v_pk_fma_f32 v[68:69], v[68:69], v[208:209], v[30:31] op_sel:[0,1,0]
	v_pk_fma_f32 v[66:67], v[66:67], v[210:211], v[34:35] op_sel_hi:[1,0,1]
	v_pk_fma_f32 v[70:71], v[226:227], v[240:241], v[70:71] op_sel:[1,0,0] neg_lo:[0,0,1] neg_hi:[0,0,1]
	v_pk_fma_f32 v[32:33], v[232:233], v[68:69], 0 op_sel:[1,0,0] op_sel_hi:[1,1,0]
	v_pk_fma_f32 v[64:65], v[64:65], v[210:211], v[70:71] op_sel:[0,1,0]
	v_pk_fma_f32 v[32:33], v[234:235], v[64:65], v[32:33] op_sel:[1,0,0]
	v_pk_mul_f32 v[34:35], v[220:221], v[28:29] op_sel_hi:[0,1]
	v_pk_fma_f32 v[34:35], v[228:229], v[240:241], v[34:35] op_sel_hi:[0,1,1] neg_lo:[0,0,1] neg_hi:[0,0,1]
	v_pk_fma_f32 v[62:63], v[62:63], v[212:213], v[34:35] op_sel_hi:[1,0,1]
	v_pk_mul_f32 v[34:35], v[220:221], v[28:29] op_sel:[1,0]
	v_pk_fma_f32 v[30:31], v[232:233], v[2:3], 0 op_sel_hi:[0,1,0]
	v_pk_fma_f32 v[34:35], v[228:229], v[240:241], v[34:35] op_sel:[1,0,0] neg_lo:[0,0,1] neg_hi:[0,0,1]
	v_pk_fma_f32 v[60:61], v[60:61], v[212:213], v[34:35] op_sel:[0,1,0]
	v_pk_mul_f32 v[34:35], v[222:223], v[28:29] op_sel_hi:[0,1]
	v_pk_fma_f32 v[30:31], v[234:235], v[66:67], v[30:31] op_sel_hi:[0,1,1]
	v_pk_fma_f32 v[34:35], v[230:231], v[240:241], v[34:35] op_sel_hi:[0,1,1] neg_lo:[0,0,1] neg_hi:[0,0,1]
	v_pk_mul_f32 v[28:29], v[222:223], v[28:29] op_sel:[1,0]
	v_pk_fma_f32 v[30:31], v[236:237], v[62:63], v[30:31] op_sel_hi:[0,1,1]
	v_pk_fma_f32 v[46:47], v[46:47], v[214:215], v[34:35] op_sel_hi:[1,0,1]
	v_pk_fma_f32 v[28:29], v[230:231], v[240:241], v[28:29] op_sel:[1,0,0] neg_lo:[0,0,1] neg_hi:[0,0,1]
	v_pk_fma_f32 v[32:33], v[236:237], v[60:61], v[32:33] op_sel:[1,0,0]
	v_pk_fma_f32 v[44:45], v[44:45], v[214:215], v[28:29] op_sel:[0,1,0]
	v_pk_fma_f32 v[28:29], v[238:239], v[46:47], v[30:31] op_sel_hi:[0,1,1]
	v_pk_fma_f32 v[30:31], v[238:239], v[44:45], v[32:33] op_sel:[1,0,0]
	v_pk_add_f32 v[28:29], v[28:29], v[30:31]
	v_add_u32_e32 v72, s22, v99
	s_nop 0
	v_add_f32_dpp v28, v28, v28 quad_perm:[1,0,3,2] row_mask:0xf bank_mask:0xf bound_ctrl:1
	v_add_f32_dpp v29, v29, v29 quad_perm:[1,0,3,2] row_mask:0xf bank_mask:0xf bound_ctrl:1
	s_nop 0
	v_add_f32_dpp v28, v28, v28 quad_perm:[2,3,0,1] row_mask:0xf bank_mask:0xf bound_ctrl:1
	v_add_f32_dpp v29, v29, v29 quad_perm:[2,3,0,1] row_mask:0xf bank_mask:0xf bound_ctrl:1
	s_nop 0
	v_add_f32_dpp v28, v28, v28 row_half_mirror row_mask:0xf bank_mask:0xf bound_ctrl:1
	v_add_f32_dpp v29, v29, v29 row_half_mirror row_mask:0xf bank_mask:0xf bound_ctrl:1
	s_and_saveexec_b64 s[20:21], s[14:15]
	ds_write_b64 v72, v[28:29] offset:51968
	s_or_b64 exec, exec, s[20:21]
	s_waitcnt lgkmcnt(1)
	v_pk_mul_f32 v[160:161], v[42:43], v[66:67] op_sel_hi:[0,1]
	v_pk_fma_f32 v[160:161], v[40:41], v[2:3], v[160:161] op_sel_hi:[0,1,1]
	v_pk_mul_f32 v[42:43], v[42:43], v[64:65] op_sel:[1,0]
	v_pk_fma_f32 v[40:41], v[40:41], v[68:69], v[42:43] op_sel:[1,0,0]
	s_waitcnt lgkmcnt(0)
	v_pk_fma_f32 v[42:43], v[36:37], v[62:63], v[160:161] op_sel_hi:[0,1,1]
	v_pk_fma_f32 v[36:37], v[36:37], v[60:61], v[40:41] op_sel:[1,0,0]
	v_pk_fma_f32 v[40:41], v[38:39], v[46:47], v[42:43] op_sel_hi:[0,1,1]
	v_pk_fma_f32 v[36:37], v[38:39], v[44:45], v[36:37] op_sel:[1,0,0]
	v_pk_add_f32 v[36:37], v[40:41], v[36:37]
	ds_read_b128 v[208:211], v1 offset:7424
	ds_read_b128 v[212:215], v1 offset:7440
	ds_read_b128 v[216:219], v1 offset:11520
	ds_read_b128 v[220:223], v1 offset:11536
	ds_read_b128 v[224:227], v1 offset:15616
	ds_read_b128 v[228:231], v1 offset:15632
	ds_read_b128 v[232:235], v1 offset:19712
	ds_read_b128 v[236:239], v1 offset:19728
	ds_read_b64 v[240:241], v73 offset:23808
	ds_read_b128 v[32:35], v74 offset:3328
	ds_read_b128 v[28:31], v74 offset:3344
	v_add_f32_dpp v36, v36, v36 quad_perm:[1,0,3,2] row_mask:0xf bank_mask:0xf bound_ctrl:1
	v_add_f32_dpp v37, v37, v37 quad_perm:[1,0,3,2] row_mask:0xf bank_mask:0xf bound_ctrl:1
	s_nop 0
	v_add_f32_dpp v36, v36, v36 quad_perm:[2,3,0,1] row_mask:0xf bank_mask:0xf bound_ctrl:1
	v_add_f32_dpp v37, v37, v37 quad_perm:[2,3,0,1] row_mask:0xf bank_mask:0xf bound_ctrl:1
	s_nop 0
	v_add_f32_dpp v36, v36, v36 row_half_mirror row_mask:0xf bank_mask:0xf bound_ctrl:1
	v_add_f32_dpp v37, v37, v37 row_half_mirror row_mask:0xf bank_mask:0xf bound_ctrl:1
	v_pk_mul_f32 v[38:39], v[108:109], v[36:37] op_sel_hi:[0,1]
	v_pk_fma_f32 v[38:39], v[116:117], v[132:133], v[38:39] op_sel_hi:[0,1,1] neg_lo:[0,0,1] neg_hi:[0,0,1]
	v_pk_fma_f32 v[2:3], v[2:3], v[100:101], v[38:39] op_sel_hi:[1,0,1]
	v_pk_mul_f32 v[38:39], v[108:109], v[36:37] op_sel:[1,0]
	v_pk_mul_f32 v[42:43], v[110:111], v[36:37] op_sel_hi:[0,1]
	v_pk_fma_f32 v[38:39], v[116:117], v[132:133], v[38:39] op_sel:[1,0,0] neg_lo:[0,0,1] neg_hi:[0,0,1]
	v_pk_fma_f32 v[42:43], v[118:119], v[132:133], v[42:43] op_sel_hi:[0,1,1] neg_lo:[0,0,1] neg_hi:[0,0,1]
	v_pk_fma_f32 v[68:69], v[68:69], v[100:101], v[38:39] op_sel:[0,1,0]
	v_pk_fma_f32 v[66:67], v[66:67], v[102:103], v[42:43] op_sel_hi:[1,0,1]
	v_pk_mul_f32 v[152:153], v[110:111], v[36:37] op_sel:[1,0]
	v_pk_fma_f32 v[152:153], v[118:119], v[132:133], v[152:153] op_sel:[1,0,0] neg_lo:[0,0,1] neg_hi:[0,0,1]
	v_pk_fma_f32 v[40:41], v[124:125], v[68:69], 0 op_sel:[1,0,0] op_sel_hi:[1,1,0]
	v_pk_fma_f32 v[64:65], v[64:65], v[102:103], v[152:153] op_sel:[0,1,0]
	v_pk_fma_f32 v[40:41], v[126:127], v[64:65], v[40:41] op_sel:[1,0,0]
	v_pk_mul_f32 v[42:43], v[112:113], v[36:37] op_sel_hi:[0,1]
	v_pk_fma_f32 v[42:43], v[120:121], v[132:133], v[42:43] op_sel_hi:[0,1,1] neg_lo:[0,0,1] neg_hi:[0,0,1]
	v_pk_fma_f32 v[62:63], v[62:63], v[104:105], v[42:43] op_sel_hi:[1,0,1]
	v_pk_mul_f32 v[42:43], v[112:113], v[36:37] op_sel:[1,0]
	v_pk_fma_f32 v[38:39], v[124:125], v[2:3], 0 op_sel_hi:[0,1,0]
	v_pk_fma_f32 v[42:43], v[120:121], v[132:133], v[42:43] op_sel:[1,0,0] neg_lo:[0,0,1] neg_hi:[0,0,1]
	v_pk_fma_f32 v[60:61], v[60:61], v[104:105], v[42:43] op_sel:[0,1,0]
	v_pk_mul_f32 v[42:43], v[114:115], v[36:37] op_sel_hi:[0,1]
	v_pk_fma_f32 v[38:39], v[126:127], v[66:67], v[38:39] op_sel_hi:[0,1,1]
	v_pk_fma_f32 v[42:43], v[122:123], v[132:133], v[42:43] op_sel_hi:[0,1,1] neg_lo:[0,0,1] neg_hi:[0,0,1]
	v_pk_mul_f32 v[36:37], v[114:115], v[36:37] op_sel:[1,0]
	v_pk_fma_f32 v[38:39], v[128:129], v[62:63], v[38:39] op_sel_hi:[0,1,1]
	v_pk_fma_f32 v[46:47], v[46:47], v[106:107], v[42:43] op_sel_hi:[1,0,1]
	v_pk_fma_f32 v[36:37], v[122:123], v[132:133], v[36:37] op_sel:[1,0,0] neg_lo:[0,0,1] neg_hi:[0,0,1]
	v_pk_fma_f32 v[40:41], v[128:129], v[60:61], v[40:41] op_sel:[1,0,0]
	v_pk_fma_f32 v[44:45], v[44:45], v[106:107], v[36:37] op_sel:[0,1,0]
	v_pk_fma_f32 v[36:37], v[130:131], v[46:47], v[38:39] op_sel_hi:[0,1,1]
	v_pk_fma_f32 v[38:39], v[130:131], v[44:45], v[40:41] op_sel:[1,0,0]
	v_pk_add_f32 v[36:37], v[36:37], v[38:39]
	s_waitcnt lgkmcnt(1)
	v_pk_mul_f32 v[160:161], v[34:35], v[66:67] op_sel_hi:[0,1]
	v_pk_fma_f32 v[160:161], v[32:33], v[2:3], v[160:161] op_sel_hi:[0,1,1]
	v_add_f32_dpp v36, v36, v36 quad_perm:[1,0,3,2] row_mask:0xf bank_mask:0xf bound_ctrl:1
	v_add_f32_dpp v37, v37, v37 quad_perm:[1,0,3,2] row_mask:0xf bank_mask:0xf bound_ctrl:1
	v_pk_mul_f32 v[34:35], v[34:35], v[64:65] op_sel:[1,0]
	v_pk_fma_f32 v[32:33], v[32:33], v[68:69], v[34:35] op_sel:[1,0,0]
	v_add_f32_dpp v36, v36, v36 quad_perm:[2,3,0,1] row_mask:0xf bank_mask:0xf bound_ctrl:1
	v_add_f32_dpp v37, v37, v37 quad_perm:[2,3,0,1] row_mask:0xf bank_mask:0xf bound_ctrl:1
	s_waitcnt lgkmcnt(0)
	v_pk_fma_f32 v[34:35], v[28:29], v[62:63], v[160:161] op_sel_hi:[0,1,1]
	v_pk_fma_f32 v[28:29], v[28:29], v[60:61], v[32:33] op_sel:[1,0,0]
	v_add_f32_dpp v36, v36, v36 row_half_mirror row_mask:0xf bank_mask:0xf bound_ctrl:1
	v_add_f32_dpp v37, v37, v37 row_half_mirror row_mask:0xf bank_mask:0xf bound_ctrl:1
	v_pk_fma_f32 v[32:33], v[30:31], v[46:47], v[34:35] op_sel_hi:[0,1,1]
	v_pk_fma_f32 v[28:29], v[30:31], v[44:45], v[28:29] op_sel:[1,0,0]
	s_and_saveexec_b64 s[20:21], s[14:15]
	ds_write_b64 v72, v[36:37] offset:52224
	s_or_b64 exec, exec, s[20:21]
	v_pk_add_f32 v[28:29], v[32:33], v[28:29]
	ds_read_b128 v[40:43], v74 offset:3584
	ds_read_b128 v[36:39], v74 offset:3600
	v_add_f32_dpp v28, v28, v28 quad_perm:[1,0,3,2] row_mask:0xf bank_mask:0xf bound_ctrl:1
	v_add_f32_dpp v29, v29, v29 quad_perm:[1,0,3,2] row_mask:0xf bank_mask:0xf bound_ctrl:1
	s_nop 0
	v_add_f32_dpp v28, v28, v28 quad_perm:[2,3,0,1] row_mask:0xf bank_mask:0xf bound_ctrl:1
	v_add_f32_dpp v29, v29, v29 quad_perm:[2,3,0,1] row_mask:0xf bank_mask:0xf bound_ctrl:1
	s_nop 0
	v_add_f32_dpp v28, v28, v28 row_half_mirror row_mask:0xf bank_mask:0xf bound_ctrl:1
	v_add_f32_dpp v29, v29, v29 row_half_mirror row_mask:0xf bank_mask:0xf bound_ctrl:1
	v_pk_mul_f32 v[30:31], v[216:217], v[28:29] op_sel_hi:[0,1]
	v_pk_fma_f32 v[30:31], v[224:225], v[240:241], v[30:31] op_sel_hi:[0,1,1] neg_lo:[0,0,1] neg_hi:[0,0,1]
	v_pk_fma_f32 v[2:3], v[2:3], v[208:209], v[30:31] op_sel_hi:[1,0,1]
	v_pk_mul_f32 v[30:31], v[216:217], v[28:29] op_sel:[1,0]
	v_pk_mul_f32 v[34:35], v[218:219], v[28:29] op_sel_hi:[0,1]
	v_pk_fma_f32 v[30:31], v[224:225], v[240:241], v[30:31] op_sel:[1,0,0] neg_lo:[0,0,1] neg_hi:[0,0,1]
	v_pk_fma_f32 v[34:35], v[226:227], v[240:241], v[34:35] op_sel_hi:[0,1,1] neg_lo:[0,0,1] neg_hi:[0,0,1]
	v_pk_fma_f32 v[68:69], v[68:69], v[208:209], v[30:31] op_sel:[0,1,0]
	v_pk_fma_f32 v[66:67], v[66:67], v[210:211], v[34:35] op_sel_hi:[1,0,1]
	v_pk_mul_f32 v[152:153], v[218:219], v[28:29] op_sel:[1,0]
	v_pk_fma_f32 v[152:153], v[226:227], v[240:241], v[152:153] op_sel:[1,0,0] neg_lo:[0,0,1] neg_hi:[0,0,1]
	v_pk_fma_f32 v[32:33], v[232:233], v[68:69], 0 op_sel:[1,0,0] op_sel_hi:[1,1,0]
	v_pk_fma_f32 v[64:65], v[64:65], v[210:211], v[152:153] op_sel:[0,1,0]
	v_pk_fma_f32 v[32:33], v[234:235], v[64:65], v[32:33] op_sel:[1,0,0]
	v_pk_mul_f32 v[34:35], v[220:221], v[28:29] op_sel_hi:[0,1]
	v_pk_fma_f32 v[34:35], v[228:229], v[240:241], v[34:35] op_sel_hi:[0,1,1] neg_lo:[0,0,1] neg_hi:[0,0,1]
	v_pk_fma_f32 v[62:63], v[62:63], v[212:213], v[34:35] op_sel_hi:[1,0,1]
	v_pk_mul_f32 v[34:35], v[220:221], v[28:29] op_sel:[1,0]
	v_pk_fma_f32 v[30:31], v[232:233], v[2:3], 0 op_sel_hi:[0,1,0]
	v_pk_fma_f32 v[34:35], v[228:229], v[240:241], v[34:35] op_sel:[1,0,0] neg_lo:[0,0,1] neg_hi:[0,0,1]
	v_pk_fma_f32 v[60:61], v[60:61], v[212:213], v[34:35] op_sel:[0,1,0]
	v_pk_mul_f32 v[34:35], v[222:223], v[28:29] op_sel_hi:[0,1]
	v_pk_fma_f32 v[30:31], v[234:235], v[66:67], v[30:31] op_sel_hi:[0,1,1]
	v_pk_fma_f32 v[34:35], v[230:231], v[240:241], v[34:35] op_sel_hi:[0,1,1] neg_lo:[0,0,1] neg_hi:[0,0,1]
	v_pk_mul_f32 v[28:29], v[222:223], v[28:29] op_sel:[1,0]
	v_pk_fma_f32 v[30:31], v[236:237], v[62:63], v[30:31] op_sel_hi:[0,1,1]
	v_pk_fma_f32 v[46:47], v[46:47], v[214:215], v[34:35] op_sel_hi:[1,0,1]
	v_pk_fma_f32 v[28:29], v[230:231], v[240:241], v[28:29] op_sel:[1,0,0] neg_lo:[0,0,1] neg_hi:[0,0,1]
	v_pk_fma_f32 v[32:33], v[236:237], v[60:61], v[32:33] op_sel:[1,0,0]
	v_pk_fma_f32 v[44:45], v[44:45], v[214:215], v[28:29] op_sel:[0,1,0]
	v_pk_fma_f32 v[28:29], v[238:239], v[46:47], v[30:31] op_sel_hi:[0,1,1]
	v_pk_fma_f32 v[30:31], v[238:239], v[44:45], v[32:33] op_sel:[1,0,0]
	v_pk_add_f32 v[28:29], v[28:29], v[30:31]
	s_nop 1
	v_add_f32_dpp v28, v28, v28 quad_perm:[1,0,3,2] row_mask:0xf bank_mask:0xf bound_ctrl:1
	v_add_f32_dpp v29, v29, v29 quad_perm:[1,0,3,2] row_mask:0xf bank_mask:0xf bound_ctrl:1
	s_nop 0
	v_add_f32_dpp v28, v28, v28 quad_perm:[2,3,0,1] row_mask:0xf bank_mask:0xf bound_ctrl:1
	v_add_f32_dpp v29, v29, v29 quad_perm:[2,3,0,1] row_mask:0xf bank_mask:0xf bound_ctrl:1
	s_nop 0
	v_add_f32_dpp v28, v28, v28 row_half_mirror row_mask:0xf bank_mask:0xf bound_ctrl:1
	v_add_f32_dpp v29, v29, v29 row_half_mirror row_mask:0xf bank_mask:0xf bound_ctrl:1
	s_and_saveexec_b64 s[20:21], s[14:15]
	ds_write_b64 v72, v[28:29] offset:52480
	s_or_b64 exec, exec, s[20:21]
	ds_read_b128 v[152:155], v1 offset:7680
	ds_read_b128 v[156:159], v1 offset:7696
	ds_read_b128 v[166:169], v1 offset:11776
	ds_read_b128 v[170:173], v1 offset:11792
	ds_read_b128 v[174:177], v1 offset:15872
	ds_read_b128 v[178:181], v1 offset:15888
	ds_read_b128 v[198:201], v1 offset:19968
	ds_read_b128 v[202:205], v1 offset:19984
	ds_read_b64 v[70:71], v73 offset:24064
	ds_read_b128 v[32:35], v74 offset:3840
	ds_read_b128 v[28:31], v74 offset:3856
	s_waitcnt lgkmcnt(12)
	v_pk_mul_f32 v[74:75], v[42:43], v[66:67] op_sel_hi:[0,1]
	v_pk_fma_f32 v[74:75], v[40:41], v[2:3], v[74:75] op_sel_hi:[0,1,1]
	v_pk_mul_f32 v[42:43], v[42:43], v[64:65] op_sel:[1,0]
	v_pk_fma_f32 v[40:41], v[40:41], v[68:69], v[42:43] op_sel:[1,0,0]
	s_waitcnt lgkmcnt(11)
	v_pk_fma_f32 v[42:43], v[36:37], v[62:63], v[74:75] op_sel_hi:[0,1,1]
	v_pk_fma_f32 v[36:37], v[36:37], v[60:61], v[40:41] op_sel:[1,0,0]
	v_pk_fma_f32 v[40:41], v[38:39], v[46:47], v[42:43] op_sel_hi:[0,1,1]
	v_pk_fma_f32 v[36:37], v[38:39], v[44:45], v[36:37] op_sel:[1,0,0]
	v_pk_add_f32 v[36:37], v[40:41], v[36:37]
	s_waitcnt lgkmcnt(10)
	s_nop 0
	v_add_f32_dpp v36, v36, v36 quad_perm:[1,0,3,2] row_mask:0xf bank_mask:0xf bound_ctrl:1
	v_add_f32_dpp v37, v37, v37 quad_perm:[1,0,3,2] row_mask:0xf bank_mask:0xf bound_ctrl:1
	s_nop 0
	v_add_f32_dpp v36, v36, v36 quad_perm:[2,3,0,1] row_mask:0xf bank_mask:0xf bound_ctrl:1
	v_add_f32_dpp v37, v37, v37 quad_perm:[2,3,0,1] row_mask:0xf bank_mask:0xf bound_ctrl:1
	s_nop 0
	v_add_f32_dpp v74, v36, v36 row_half_mirror row_mask:0xf bank_mask:0xf bound_ctrl:1
	v_add_f32_dpp v75, v37, v37 row_half_mirror row_mask:0xf bank_mask:0xf bound_ctrl:1
	s_waitcnt lgkmcnt(8)
	v_pk_mul_f32 v[36:37], v[166:167], v[74:75] op_sel_hi:[0,1]
	s_waitcnt lgkmcnt(2)
	v_pk_fma_f32 v[36:37], v[174:175], v[70:71], v[36:37] op_sel_hi:[0,1,1] neg_lo:[0,0,1] neg_hi:[0,0,1]
	v_pk_mul_f32 v[38:39], v[168:169], v[74:75] op_sel_hi:[0,1]
	v_pk_fma_f32 v[2:3], v[2:3], v[152:153], v[36:37] op_sel_hi:[1,0,1]
	v_pk_mul_f32 v[36:37], v[166:167], v[74:75] op_sel:[1,0]
	v_pk_fma_f32 v[38:39], v[176:177], v[70:71], v[38:39] op_sel_hi:[0,1,1] neg_lo:[0,0,1] neg_hi:[0,0,1]
	v_pk_fma_f32 v[36:37], v[174:175], v[70:71], v[36:37] op_sel:[1,0,0] neg_lo:[0,0,1] neg_hi:[0,0,1]
	v_pk_fma_f32 v[38:39], v[66:67], v[154:155], v[38:39] op_sel_hi:[1,0,1]
	v_pk_fma_f32 v[36:37], v[68:69], v[152:153], v[36:37] op_sel:[0,1,0]
	v_pk_mul_f32 v[66:67], v[168:169], v[74:75] op_sel:[1,0]
	v_pk_fma_f32 v[42:43], v[198:199], v[2:3], 0 op_sel_hi:[0,1,0]
	v_pk_fma_f32 v[66:67], v[176:177], v[70:71], v[66:67] op_sel:[1,0,0] neg_lo:[0,0,1] neg_hi:[0,0,1]
	v_pk_fma_f32 v[68:69], v[198:199], v[36:37], 0 op_sel:[1,0,0] op_sel_hi:[1,1,0]
	v_pk_fma_f32 v[40:41], v[64:65], v[154:155], v[66:67] op_sel:[0,1,0]
	v_pk_fma_f32 v[64:65], v[200:201], v[38:39], v[42:43] op_sel_hi:[0,1,1]
	v_pk_fma_f32 v[66:67], v[200:201], v[40:41], v[68:69] op_sel:[1,0,0]
	v_pk_mul_f32 v[42:43], v[170:171], v[74:75] op_sel_hi:[0,1]
	v_pk_fma_f32 v[42:43], v[178:179], v[70:71], v[42:43] op_sel_hi:[0,1,1] neg_lo:[0,0,1] neg_hi:[0,0,1]
	v_pk_fma_f32 v[42:43], v[62:63], v[156:157], v[42:43] op_sel_hi:[1,0,1]
	v_pk_mul_f32 v[62:63], v[170:171], v[74:75] op_sel:[1,0]
	v_pk_fma_f32 v[62:63], v[178:179], v[70:71], v[62:63] op_sel:[1,0,0] neg_lo:[0,0,1] neg_hi:[0,0,1]
	v_pk_fma_f32 v[60:61], v[60:61], v[156:157], v[62:63] op_sel:[0,1,0]
	v_pk_fma_f32 v[62:63], v[202:203], v[42:43], v[64:65] op_sel_hi:[0,1,1]
	v_pk_fma_f32 v[64:65], v[202:203], v[60:61], v[66:67] op_sel:[1,0,0]
	v_pk_mul_f32 v[66:67], v[172:173], v[74:75] op_sel_hi:[0,1]
	v_pk_fma_f32 v[66:67], v[180:181], v[70:71], v[66:67] op_sel_hi:[0,1,1] neg_lo:[0,0,1] neg_hi:[0,0,1]
	v_pk_mul_f32 v[68:69], v[172:173], v[74:75] op_sel:[1,0]
	v_pk_fma_f32 v[46:47], v[46:47], v[158:159], v[66:67] op_sel_hi:[1,0,1]
	v_pk_fma_f32 v[68:69], v[180:181], v[70:71], v[68:69] op_sel:[1,0,0] neg_lo:[0,0,1] neg_hi:[0,0,1]
	v_pk_fma_f32 v[44:45], v[44:45], v[158:159], v[68:69] op_sel:[0,1,0]
	v_pk_fma_f32 v[62:63], v[204:205], v[46:47], v[62:63] op_sel_hi:[0,1,1]
	v_pk_fma_f32 v[64:65], v[204:205], v[44:45], v[64:65] op_sel:[1,0,0]
	v_pk_add_f32 v[62:63], v[62:63], v[64:65]
	s_waitcnt lgkmcnt(1)
	v_pk_mul_f32 v[66:67], v[34:35], v[38:39] op_sel_hi:[0,1]
	v_pk_mul_f32 v[68:69], v[34:35], v[40:41] op_sel:[1,0]
	v_add_f32_dpp v62, v62, v62 quad_perm:[1,0,3,2] row_mask:0xf bank_mask:0xf bound_ctrl:1
	v_add_f32_dpp v63, v63, v63 quad_perm:[1,0,3,2] row_mask:0xf bank_mask:0xf bound_ctrl:1
	v_pk_fma_f32 v[66:67], v[32:33], v[2:3], v[66:67] op_sel_hi:[0,1,1]
	v_pk_fma_f32 v[68:69], v[32:33], v[36:37], v[68:69] op_sel:[1,0,0]
	v_add_f32_dpp v62, v62, v62 quad_perm:[2,3,0,1] row_mask:0xf bank_mask:0xf bound_ctrl:1
	v_add_f32_dpp v63, v63, v63 quad_perm:[2,3,0,1] row_mask:0xf bank_mask:0xf bound_ctrl:1
	s_waitcnt lgkmcnt(0)
	v_pk_fma_f32 v[66:67], v[28:29], v[42:43], v[66:67] op_sel_hi:[0,1,1]
	v_pk_fma_f32 v[68:69], v[28:29], v[60:61], v[68:69] op_sel:[1,0,0]
	v_add_f32_dpp v62, v62, v62 row_half_mirror row_mask:0xf bank_mask:0xf bound_ctrl:1
	v_add_f32_dpp v63, v63, v63 row_half_mirror row_mask:0xf bank_mask:0xf bound_ctrl:1
	v_pk_fma_f32 v[66:67], v[30:31], v[46:47], v[66:67] op_sel_hi:[0,1,1]
	v_pk_fma_f32 v[68:69], v[30:31], v[44:45], v[68:69] op_sel:[1,0,0]
	s_and_saveexec_b64 s[20:21], s[14:15]
	ds_write_b64 v72, v[62:63] offset:52736
	s_or_b64 exec, exec, s[20:21]
	v_pk_add_f32 v[66:67], v[66:67], v[68:69]
	ds_read_b64 v[74:75], v73 offset:24320
	ds_read_b128 v[152:155], v1 offset:20240
	ds_read_b128 v[156:159], v1 offset:20224
	ds_read_b128 v[166:169], v1 offset:16144
	ds_read_b128 v[62:65], v1 offset:16128
	ds_read_b128 v[170:173], v1 offset:12048
	ds_read_b128 v[174:177], v1 offset:12032
	ds_read_b128 v[178:181], v1 offset:7936
	ds_read_b128 v[198:201], v1 offset:7952
	v_add_f32_dpp v66, v66, v66 quad_perm:[1,0,3,2] row_mask:0xf bank_mask:0xf bound_ctrl:1
	v_add_f32_dpp v67, v67, v67 quad_perm:[1,0,3,2] row_mask:0xf bank_mask:0xf bound_ctrl:1
	s_nop 0
	v_add_f32_dpp v66, v66, v66 quad_perm:[2,3,0,1] row_mask:0xf bank_mask:0xf bound_ctrl:1
	v_add_f32_dpp v67, v67, v67 quad_perm:[2,3,0,1] row_mask:0xf bank_mask:0xf bound_ctrl:1
	s_nop 0
	v_add_f32_dpp v160, v66, v66 row_half_mirror row_mask:0xf bank_mask:0xf bound_ctrl:1
	v_add_f32_dpp v161, v67, v67 row_half_mirror row_mask:0xf bank_mask:0xf bound_ctrl:1
	s_waitcnt lgkmcnt(2)
	v_pk_mul_f32 v[66:67], v[174:175], v[160:161] op_sel_hi:[0,1]
	v_pk_fma_f32 v[66:67], v[74:75], v[62:63], v[66:67] op_sel_hi:[1,0,1] neg_lo:[0,0,1] neg_hi:[0,0,1]
	s_waitcnt lgkmcnt(1)
	v_pk_fma_f32 v[70:71], v[2:3], v[178:179], v[66:67] op_sel_hi:[1,0,1]
	v_pk_mul_f32 v[2:3], v[174:175], v[160:161] op_sel:[1,0]
	s_nop 0
	v_pk_fma_f32 v[2:3], v[74:75], v[62:63], v[2:3] op_sel:[0,1,0] neg_lo:[0,0,1] neg_hi:[0,0,1]
	v_pk_mul_f32 v[62:63], v[176:177], v[160:161] op_sel_hi:[0,1]
	v_pk_fma_f32 v[62:63], v[74:75], v[64:65], v[62:63] op_sel_hi:[1,0,1] neg_lo:[0,0,1] neg_hi:[0,0,1]
	v_pk_fma_f32 v[66:67], v[38:39], v[180:181], v[62:63] op_sel_hi:[1,0,1]
	v_pk_mul_f32 v[62:63], v[176:177], v[160:161] op_sel:[1,0]
	v_pk_fma_f32 v[68:69], v[36:37], v[178:179], v[2:3] op_sel:[0,1,0]
	v_pk_fma_f32 v[62:63], v[74:75], v[64:65], v[62:63] op_sel:[0,1,0] neg_lo:[0,0,1] neg_hi:[0,0,1]
	v_pk_fma_f32 v[36:37], v[156:157], v[68:69], 0 op_sel:[1,0,0] op_sel_hi:[1,1,0]
	v_pk_fma_f32 v[64:65], v[40:41], v[180:181], v[62:63] op_sel:[0,1,0]
	v_pk_fma_f32 v[36:37], v[158:159], v[64:65], v[36:37] op_sel:[1,0,0]
	v_pk_mul_f32 v[38:39], v[170:171], v[160:161] op_sel_hi:[0,1]
	v_pk_fma_f32 v[38:39], v[74:75], v[166:167], v[38:39] op_sel_hi:[1,0,1] neg_lo:[0,0,1] neg_hi:[0,0,1]
	s_waitcnt lgkmcnt(0)
	v_pk_fma_f32 v[62:63], v[42:43], v[198:199], v[38:39] op_sel_hi:[1,0,1]
	v_pk_mul_f32 v[38:39], v[170:171], v[160:161] op_sel:[1,0]
	v_pk_fma_f32 v[2:3], v[156:157], v[70:71], 0 op_sel_hi:[0,1,0]
	v_pk_fma_f32 v[38:39], v[74:75], v[166:167], v[38:39] op_sel:[0,1,0] neg_lo:[0,0,1] neg_hi:[0,0,1]
	v_mov_b32_e32 v42, v169
	v_pk_fma_f32 v[60:61], v[60:61], v[198:199], v[38:39] op_sel:[0,1,0]
	v_pk_mul_f32 v[38:39], v[172:173], v[160:161] op_sel_hi:[0,1]
	v_pk_fma_f32 v[38:39], v[74:75], v[168:169], v[38:39] op_sel_hi:[1,0,1] neg_lo:[0,0,1] neg_hi:[0,0,1]
	v_pk_mul_f32 v[40:41], v[172:173], v[160:161] op_sel:[1,0]
	v_pk_fma_f32 v[2:3], v[158:159], v[66:67], v[2:3] op_sel_hi:[0,1,1]
	v_pk_fma_f32 v[46:47], v[46:47], v[200:201], v[38:39] op_sel_hi:[1,0,1]
	v_pk_fma_f32 v[40:41], v[74:75], v[42:43], v[40:41] op_sel_hi:[1,0,1] neg_lo:[0,0,1] neg_hi:[0,0,1]
	v_pk_fma_f32 v[2:3], v[152:153], v[62:63], v[2:3] op_sel_hi:[0,1,1]
	v_pk_fma_f32 v[36:37], v[152:153], v[60:61], v[36:37] op_sel:[1,0,0]
	v_pk_fma_f32 v[44:45], v[44:45], v[200:201], v[40:41] op_sel:[0,1,0]
	v_mov_b32_e32 v38, v155
	v_pk_fma_f32 v[2:3], v[154:155], v[46:47], v[2:3] op_sel_hi:[0,1,1]
	v_pk_fma_f32 v[36:37], v[38:39], v[44:45], v[36:37] op_sel_hi:[0,1,1]
	v_pk_add_f32 v[2:3], v[2:3], v[36:37]
	s_nop 1
	v_add_f32_dpp v2, v2, v2 quad_perm:[1,0,3,2] row_mask:0xf bank_mask:0xf bound_ctrl:1
	v_add_f32_dpp v3, v3, v3 quad_perm:[1,0,3,2] row_mask:0xf bank_mask:0xf bound_ctrl:1
	s_nop 0
	v_add_f32_dpp v2, v2, v2 quad_perm:[2,3,0,1] row_mask:0xf bank_mask:0xf bound_ctrl:1
	v_add_f32_dpp v3, v3, v3 quad_perm:[2,3,0,1] row_mask:0xf bank_mask:0xf bound_ctrl:1
	s_nop 0
	v_mov_b32_dpp v36, v2 row_half_mirror row_mask:0xf bank_mask:0xf bound_ctrl:1
	v_mov_b32_dpp v37, v3 row_half_mirror row_mask:0xf bank_mask:0xf bound_ctrl:1
	s_and_saveexec_b64 s[20:21], s[14:15]
	s_cbranch_execz .LBB0_575
	v_pk_add_f32 v[2:3], v[2:3], v[36:37]
	ds_write_b64 v72, v[2:3] offset:52992
	s_branch .LBB0_575
